# third ctx-row partial-sum copy batched; rowwise H-part loads hoisted; transposes rebalanced over scan phases and GEMM tails
# speedup vs baseline: 1.0243x; 1.0105x over previous
; __device__ __forceinline__ float dot4(f32x4 a) { return (a.x * a.x + a.y * a.y) + (a.z * a.z + a.w * a.w); }
; __device__ __forceinline__ void rowwise_phase(const Params& P, int mrows, bool first, int l_post, int j_post, int gate_idx, float coef, bool final_, int l_pre, int j_pre, int shift_idx, int scale_idx) {
;     ...
;             const float* gp = P.norm_post + (size_t)(l_post * 3 + j_post) * DM; const float* mg = MOD + (size_t)(l_post * 5 + b) * NMODV + gate_idx * DM;
;             float sxx = 0.f, sxt = 0.f, stt = 0.f;
; #pragma unroll
;             for (int j = 0; j < 8; ++j) { const int c = 4 * lane + 256 * j; xv[j] = *(const f32x4*)(xr + c); const f32x4 g4 = *(const f32x4*)(gp + c), m4 = *(const f32x4*)(mg + c);
;                 ss += dot4(yv[j]); yv[j] = yv[j] * g4 * m4; sxx += dot4(xv[j]); stt += dot4(yv[j]);
;                 const f32x4 xt = xv[j] * yv[j]; sxt += (xt.x + xt.y) + (xt.z + xt.w); }
.LBB0_25:
	v_lshl_add_u64 v[120:121], s[94:95], 0, v[116:117]
	s_mov_b32 s3, 0x14e01000
	v_add_co_u32_e32 v122, vcc, s3, v120
	global_load_dwordx4 v[56:59], v[92:93], off
	s_nop 0
	v_addc_co_u32_e32 v123, vcc, 0, v121, vcc
	s_mov_b32 s3, 0x14e00000
	s_min_i32 s5, s4, 0x2000
	v_readlane_b32 s14, v255, 14
	v_add_co_u32_e32 v52, vcc, s3, v120
	s_ashr_i32 s5, s5, 11
	s_mul_i32 s9, s14, 5
	global_load_dwordx4 v[60:63], v[92:93], off offset:1024
	global_load_dwordx4 v[76:79], v[92:93], off offset:2048
	global_load_dwordx4 v[40:43], v[122:123], off offset:-4096
	v_addc_co_u32_e32 v53, vcc, 0, v121, vcc
	s_add_i32 s5, s5, s9
	global_load_dwordx4 v[44:47], v[52:53], off offset:1024
	global_load_dwordx4 v[36:39], v[52:53], off offset:2048
	s_mul_i32 s14, s5, 0x12000
	v_readlane_b32 s15, v255, 15
	s_mul_hi_i32 s9, s5, 0x12000
	s_add_u32 s14, s20, s14
	v_lshlrev_b32_e32 v145, 2, v0
	s_addc_u32 s15, s21, s9
	s_nop 0
	global_load_dwordx4 v[72:75], v145, s[14:15]
	global_load_dwordx4 v[68:71], v145, s[14:15] offset:1024
	global_load_dwordx4 v[64:67], v145, s[14:15] offset:2048
	s_waitcnt vmcnt(0)
	v_pk_mul_f32 v[48:49], v[18:19], v[18:19]
	v_pk_mul_f32 v[50:51], v[16:17], v[16:17]
	s_waitcnt lgkmcnt(0)
	global_load_dwordx4 v[80:83], v[92:93], off offset:3072
	global_load_dwordx4 v[84:87], v[94:95], off
	v_pk_mov_b32 v[54:55], v[50:51], v[48:49] op_sel:[1,0]
	v_mov_b32_e32 v51, v49
	v_pk_add_f32 v[54:55], v[54:55], v[50:51]
	global_load_dwordx4 v[48:51], v[122:123], off
	v_pk_add_f32 v[128:129], v[54:55], v[54:55] op_sel_hi:[0,1]
	global_load_dwordx4 v[52:55], v[52:53], off offset:3072
	s_nop 0
	global_load_dwordx4 v[146:149], v145, s[14:15] offset:3072
	global_load_dwordx4 v[88:91], v138, s[14:15]
	global_load_dwordx4 v[150:153], v141, s[14:15]
	v_mov_b32_e32 v125, v4
	v_mov_b32_e32 v127, v6
	v_mov_b32_e32 v124, v8
	v_mov_b32_e32 v126, v10
	global_load_dwordx4 v[154:157], v139, s[14:15]
	v_mul_f32_e32 v128, v22, v22
	s_mov_b32 s3, 0x800000
	s_waitcnt vmcnt(16)
	v_pk_mul_f32 v[58:59], v[6:7], v[58:59]
	v_pk_mul_f32 v[56:57], v[4:5], v[56:57]
	v_mov_b32_e32 v4, v9
	v_mov_b32_e32 v6, v11
	v_pk_mul_f32 v[4:5], v[4:5], v[4:5]
	v_pk_mul_f32 v[6:7], v[6:7], v[6:7]
	v_pk_fma_f32 v[4:5], v[124:125], v[124:125], v[4:5]
	v_pk_fma_f32 v[6:7], v[126:127], v[126:127], v[6:7]
	s_waitcnt vmcnt(15)
	v_pk_mul_f32 v[62:63], v[10:11], v[62:63]
	v_pk_mul_f32 v[60:61], v[8:9], v[60:61]
	s_waitcnt vmcnt(13)
	v_mul_f32_e32 v2, v41, v41
	v_mul_f32_e32 v8, v42, v42
	v_fmac_f32_e32 v2, v40, v40
	s_waitcnt vmcnt(12)
	v_mul_f32_e32 v9, v45, v45
	v_mul_f32_e32 v10, v46, v46
	v_fmac_f32_e32 v8, v43, v43
	v_pk_add_f32 v[4:5], v[4:5], v[6:7]
	v_fmac_f32_e32 v9, v44, v44
	v_fmac_f32_e32 v10, v47, v47
	v_add_f32_e32 v2, v2, v8
	v_pk_add_f32 v[6:7], v[4:5], v[4:5] op_sel_hi:[0,1]
	v_add_f32_e32 v4, v9, v10
	v_pk_mul_f32 v[18:19], v[18:19], v[78:79]
	v_pk_mul_f32 v[76:77], v[16:17], v[76:77]
	v_add_f32_e32 v6, v2, v4
	s_waitcnt vmcnt(10)
	v_pk_mul_f32 v[4:5], v[74:75], v[58:59]
	v_pk_mul_f32 v[10:11], v[72:73], v[56:57]
	s_waitcnt vmcnt(9)
	v_pk_mul_f32 v[8:9], v[70:71], v[62:63]
	v_pk_mul_f32 v[68:69], v[68:69], v[60:61]
	s_waitcnt vmcnt(8)
	v_pk_mul_f32 v[16:17], v[66:67], v[18:19]
	v_pk_mul_f32 v[18:19], v[64:65], v[76:77]
	v_mul_f32_e32 v2, v5, v5
	v_pk_mul_f32 v[60:61], v[42:43], v[4:5]
	v_pk_mul_f32 v[62:63], v[40:41], v[10:11]
	v_pk_mul_f32 v[74:75], v[46:47], v[8:9]
	v_pk_mul_f32 v[76:77], v[44:45], v[68:69]
	v_mul_f32_e32 v56, v10, v10
	v_mul_f32_e32 v58, v11, v11
	v_mul_f32_e32 v64, v68, v68
	v_mul_f32_e32 v66, v69, v69
	v_mul_f32_e32 v70, v8, v8
	v_mul_f32_e32 v72, v9, v9
	v_pk_fma_f32 v[78:79], v[4:5], v[4:5], v[2:3] op_sel_hi:[1,1,0]
	v_add_f32_e32 v57, v62, v63
	v_add_f32_e32 v59, v60, v61
	v_mov_b32_e32 v65, v76
	v_mov_b32_e32 v67, v77
	v_mov_b32_e32 v71, v74
	v_mov_b32_e32 v73, v75
	v_mul_f32_e32 v124, v37, v37
	v_mul_f32_e32 v2, v38, v38
	v_pk_mul_f32 v[162:163], v[38:39], v[16:17]
	v_pk_mul_f32 v[164:165], v[36:37], v[18:19]
	v_pk_add_f32 v[56:57], v[56:57], v[58:59]
	v_mov_b32_e32 v79, v3
	v_pk_add_f32 v[58:59], v[64:65], v[66:67]
	v_pk_add_f32 v[64:65], v[70:71], v[72:73]
	v_fmac_f32_e32 v124, v36, v36
	v_fmac_f32_e32 v2, v39, v39
	v_mul_f32_e32 v60, v18, v18
	v_mul_f32_e32 v62, v19, v19
	v_mul_f32_e32 v158, v16, v16
	v_mul_f32_e32 v160, v17, v17
	v_pk_add_f32 v[56:57], v[56:57], v[78:79]
	v_pk_add_f32 v[58:59], v[58:59], v[64:65]
	v_mov_b32_e32 v61, v164
	v_mov_b32_e32 v63, v165
	v_mov_b32_e32 v159, v162
	v_mov_b32_e32 v161, v163
	v_add_f32_e32 v2, v124, v2
	v_pk_add_f32 v[64:65], v[56:57], v[58:59]
	global_load_dwordx4 v[56:59], v[122:123], off offset:1024
	v_pk_add_f32 v[60:61], v[60:61], v[62:63]
	v_pk_add_f32 v[62:63], v[158:159], v[160:161]
	v_add_f32_e32 v6, v6, v2
	v_pk_add_f32 v[60:61], v[60:61], v[62:63]
	v_mul_f32_e32 v2, v12, v12
	v_pk_add_f32 v[158:159], v[64:65], v[60:61]
	v_pk_fma_f32 v[64:65], v[12:13], v[12:13], v[2:3] op_sel_hi:[1,1,0]
	v_mul_f32_e32 v2, v14, v14
	v_pk_fma_f32 v[66:67], v[14:15], v[14:15], v[2:3] op_sel_hi:[1,1,0]
	s_waitcnt vmcnt(8)
	v_pk_mul_f32 v[14:15], v[14:15], v[82:83]
	v_pk_mul_f32 v[12:13], v[12:13], v[80:81]
	global_load_dwordx4 v[124:127], v[96:97], off
	s_waitcnt vmcnt(5)
; __device__ __forceinline__ float dot4(f32x4 a) { return (a.x * a.x + a.y * a.y) + (a.z * a.z + a.w * a.w); }
; __device__ __forceinline__ void rowwise_phase(const Params& P, int mrows, bool first, int l_post, int j_post, int gate_idx, float coef, bool final_, int l_pre, int j_pre, int shift_idx, int scale_idx) {
;     ...
;             for (int j = 0; j < 8; ++j) { const int c = 4 * lane + 256 * j; xv[j] = *(const f32x4*)(xr + c); const f32x4 g4 = *(const f32x4*)(gp + c), m4 = *(const f32x4*)(mg + c);
;                 ss += dot4(yv[j]); yv[j] = yv[j] * g4 * m4; sxx += dot4(xv[j]); stt += dot4(yv[j]);
;                 const f32x4 xt = xv[j] * yv[j]; sxt += (xt.x + xt.y) + (xt.z + xt.w); }
; #pragma unroll
;             for (int o = 1; o < 64; o <<= 1) { ss += __shfl_xor(ss, o); sxx += __shfl_xor(sxx, o); sxt += __shfl_xor(sxt, o); stt += __shfl_xor(stt, o); }
	v_pk_mul_f32 v[70:71], v[148:149], v[14:15]
	v_pk_mul_f32 v[72:73], v[146:147], v[12:13]
	global_load_dwordx4 v[12:15], v[98:99], off
	global_load_dwordx4 v[78:81], v140, s[14:15]
	global_load_dwordx4 v[60:63], v[122:123], off offset:2048
	v_mul_f32_e32 v2, v53, v53
	v_mul_f32_e32 v64, v54, v54
	v_pk_mul_f32 v[148:149], v[54:55], v[70:71]
	v_pk_mul_f32 v[160:161], v[52:53], v[72:73]
	v_fmac_f32_e32 v2, v52, v52
	v_fmac_f32_e32 v64, v55, v55
	v_mul_f32_e32 v74, v72, v72
	v_mul_f32_e32 v76, v73, v73
	v_mul_f32_e32 v82, v70, v70
	v_mul_f32_e32 v146, v71, v71
	v_mov_b32_e32 v75, v160
	v_mov_b32_e32 v77, v161
	v_mov_b32_e32 v83, v148
	v_mov_b32_e32 v147, v149
	v_add_f32_e32 v2, v2, v64
	v_pk_add_f32 v[74:75], v[74:75], v[76:77]
	v_pk_add_f32 v[76:77], v[82:83], v[146:147]
	v_mul_f32_e32 v64, v20, v20
	v_mul_f32_e32 v66, v21, v21
	global_load_dwordx4 v[146:149], v[100:101], off
	v_pk_add_f32 v[82:83], v[74:75], v[76:77]
	v_pk_add_f32 v[74:75], v[64:65], v[66:67]
	global_load_dwordx4 v[64:67], v[122:123], off offset:3072
	v_add_f32_e32 v2, v6, v2
	v_mul_f32_e32 v6, v23, v23
	v_pk_add_f32 v[6:7], v[128:129], v[6:7]
	v_pk_mul_f32 v[22:23], v[22:23], v[86:87]
	v_pk_add_f32 v[6:7], v[74:75], v[6:7]
	v_pk_mul_f32 v[20:21], v[20:21], v[84:85]
	v_pk_add_f32 v[6:7], v[6:7], v[6:7] op_sel_hi:[0,1]
	s_waitcnt vmcnt(9)
	v_pk_mul_f32 v[74:75], v[90:91], v[22:23]
	v_pk_mul_f32 v[76:77], v[88:89], v[20:21]
	v_mul_f32_e32 v6, v49, v49
	v_mul_f32_e32 v20, v50, v50
	v_fmac_f32_e32 v6, v48, v48
	v_fmac_f32_e32 v20, v51, v51
	v_pk_mul_f32 v[88:89], v[50:51], v[74:75]
	v_pk_mul_f32 v[90:91], v[48:49], v[76:77]
	v_add_f32_e32 v6, v6, v20
	v_mul_f32_e32 v20, v76, v76
	v_mul_f32_e32 v22, v77, v77
	v_mul_f32_e32 v84, v74, v74
	v_mul_f32_e32 v86, v75, v75
	v_mov_b32_e32 v21, v90
	v_mov_b32_e32 v23, v91
	v_mov_b32_e32 v85, v88
	v_mov_b32_e32 v87, v89
	v_pk_add_f32 v[20:21], v[20:21], v[22:23]
	v_pk_add_f32 v[22:23], v[84:85], v[86:87]
	v_pk_mul_f32 v[84:85], v[26:27], v[26:27]
	v_pk_mul_f32 v[86:87], v[24:25], v[24:25]
	v_add_f32_e32 v2, v2, v6
	v_pk_mov_b32 v[88:89], v[86:87], v[84:85] op_sel:[1,0]
	v_mov_b32_e32 v87, v85
	v_pk_add_f32 v[84:85], v[88:89], v[86:87]
	v_pk_add_f32 v[82:83], v[158:159], v[82:83]
	v_pk_add_f32 v[84:85], v[84:85], v[84:85] op_sel_hi:[0,1]
	v_pk_add_f32 v[20:21], v[20:21], v[22:23]
	s_mov_b64 s[14:15], -1
	v_pk_add_f32 v[20:21], v[82:83], v[20:21]
	s_waitcnt vmcnt(6)
	v_mul_f32_e32 v6, v57, v57
	v_mul_f32_e32 v84, v58, v58
	v_fmac_f32_e32 v6, v56, v56
	v_fmac_f32_e32 v84, v59, v59
	v_add_f32_e32 v6, v6, v84
	v_add_f32_e32 v6, v2, v6
	v_mul_f32_e32 v2, v28, v28
	v_pk_fma_f32 v[128:129], v[28:29], v[28:29], v[2:3] op_sel_hi:[1,1,0]
	v_mul_f32_e32 v2, v30, v30
	v_mul_f32_e32 v128, v32, v32
	v_mul_f32_e32 v84, v34, v34
	s_waitcnt vmcnt(5)
	v_pk_mul_f32 v[26:27], v[26:27], v[126:127]
	v_pk_mul_f32 v[24:25], v[24:25], v[124:125]
	v_pk_mul_f32 v[26:27], v[156:157], v[26:27]
	s_waitcnt vmcnt(4)
	v_pk_mul_f32 v[12:13], v[28:29], v[12:13]
	v_pk_mul_f32 v[24:25], v[154:155], v[24:25]
	v_pk_fma_f32 v[154:155], v[30:31], v[30:31], v[2:3] op_sel_hi:[1,1,0]
	s_waitcnt vmcnt(3)
	v_pk_mul_f32 v[156:157], v[78:79], v[12:13]
	s_waitcnt vmcnt(2)
	v_mul_f32_e32 v2, v61, v61
	v_mul_f32_e32 v12, v62, v62
	v_fmac_f32_e32 v2, v60, v60
	v_fmac_f32_e32 v12, v63, v63
	v_add_f32_e32 v2, v2, v12
	v_add_f32_e32 v2, v6, v2
	v_mul_f32_e32 v154, v33, v33
	v_mul_f32_e32 v6, v35, v35
	v_pk_add_f32 v[128:129], v[128:129], v[154:155]
	v_pk_add_f32 v[6:7], v[84:85], v[6:7]
	v_pk_mul_f32 v[14:15], v[30:31], v[14:15]
	v_pk_add_f32 v[6:7], v[128:129], v[6:7]
	v_pk_mul_f32 v[124:125], v[58:59], v[26:27]
	v_add_f32_e32 v13, v6, v7
	v_pk_mul_f32 v[126:127], v[56:57], v[24:25]
	v_pk_mul_f32 v[28:29], v[80:81], v[14:15]
	v_mul_f32_e32 v86, v24, v24
	v_mul_f32_e32 v88, v25, v25
	s_waitcnt vmcnt(1)
	v_pk_mul_f32 v[6:7], v[34:35], v[148:149]
	v_pk_mul_f32 v[32:33], v[32:33], v[146:147]
	v_pk_mul_f32 v[34:35], v[152:153], v[6:7]
	s_waitcnt vmcnt(0)
	v_mul_f32_e32 v6, v65, v65
	v_mul_f32_e32 v7, v66, v66
	v_fmac_f32_e32 v6, v64, v64
	v_fmac_f32_e32 v7, v67, v67
	v_add_f32_e32 v6, v6, v7
	ds_bpermute_b32 v7, v1, v13
	v_mul_f32_e32 v90, v26, v26
	v_mul_f32_e32 v122, v27, v27
	v_pk_mul_f32 v[80:81], v[62:63], v[28:29]
	v_pk_mul_f32 v[160:161], v[60:61], v[156:157]
	v_pk_mul_f32 v[32:33], v[150:151], v[32:33]
	v_mov_b32_e32 v87, v126
	v_mov_b32_e32 v89, v127
	v_mov_b32_e32 v91, v124
	v_mov_b32_e32 v123, v125
	v_mul_f32_e32 v12, v156, v156
	v_mul_f32_e32 v14, v157, v157
	v_mul_f32_e32 v30, v28, v28
	v_mul_f32_e32 v78, v29, v29
	v_pk_mul_f32 v[148:149], v[66:67], v[34:35]
	v_pk_mul_f32 v[150:151], v[64:65], v[32:33]
	s_waitcnt lgkmcnt(0)
	v_add_f32_e32 v132, v13, v7
	v_pk_add_f32 v[22:23], v[86:87], v[88:89]
	v_pk_add_f32 v[82:83], v[90:91], v[122:123]
	v_mov_b32_e32 v13, v160
	v_mov_b32_e32 v15, v161
	v_mov_b32_e32 v31, v80
	v_mov_b32_e32 v79, v81
	v_add_f32_e32 v2, v2, v6
	v_mul_f32_e32 v6, v32, v32
	v_mul_f32_e32 v84, v33, v33
	v_mul_f32_e32 v128, v34, v34
	v_mul_f32_e32 v146, v35, v35
	v_pk_add_f32 v[22:23], v[22:23], v[82:83]
	v_pk_add_f32 v[12:13], v[12:13], v[14:15]
	v_pk_add_f32 v[14:15], v[30:31], v[78:79]
	v_mov_b32_e32 v7, v150
	v_mov_b32_e32 v85, v151
	v_mov_b32_e32 v129, v148
	v_mov_b32_e32 v147, v149
	v_pk_add_f32 v[20:21], v[20:21], v[22:23]
	v_pk_add_f32 v[12:13], v[12:13], v[14:15]
	v_pk_add_f32 v[6:7], v[6:7], v[84:85]
	v_pk_add_f32 v[14:15], v[128:129], v[146:147]
	v_pk_add_f32 v[12:13], v[20:21], v[12:13]
	v_pk_add_f32 v[6:7], v[6:7], v[14:15]
	ds_bpermute_b32 v153, v130, v132
	v_pk_add_f32 v[6:7], v[12:13], v[6:7]
	ds_bpermute_b32 v13, v1, v7
	ds_bpermute_b32 v12, v1, v6
	ds_bpermute_b32 v152, v1, v2
	s_waitcnt lgkmcnt(3)
; __device__ __forceinline__ float dot4(f32x4 a) { return (a.x * a.x + a.y * a.y) + (a.z * a.z + a.w * a.w); }
; __device__ __forceinline__ void rowwise_phase(const Params& P, int mrows, bool first, int l_post, int j_post, int gate_idx, float coef, bool final_, int l_pre, int j_pre, int shift_idx, int scale_idx) {
;     ...
;             for (int o = 1; o < 64; o <<= 1) { ss += __shfl_xor(ss, o); sxx += __shfl_xor(sxx, o); sxt += __shfl_xor(sxt, o); stt += __shfl_xor(stt, o); }
;             const float rs = rsqrtf(ss * (1.f / DM) + EPS) * coef;
;             ss_new = sxx + 2.f * rs * sxt + rs * rs * stt;
; #pragma unroll
;             for (int j = 0; j < 8; ++j) xv[j] += yv[j] * rs;
;         }
;         if (final_) {
;             float* o = P.out + (size_t)row * DM;
; #pragma unroll
;             for (int j = 0; j < 8; ++j) *(f32x4*)(o + 4 * lane + 256 * j) = xv[j];
;             continue;
;         }
;         {
;             float* xr = X + (size_t)row * DM; float ss = 0.f;
; #pragma unroll
;             for (int j = 0; j < 8; ++j) { if (!first) *(f32x4*)(xr + 4 * lane + 256 * j) = xv[j]; else ss += dot4(xv[j]); }
;             if (first) ss = wave_sum(ss); else ss = ss_new;
;             const float rs = rsqrtf(ss * (1.f / DM) + EPS);
;             const float* gp = P.norm_pre + (size_t)(l_pre * 3 + j_pre) * DM; const float* mb = MOD + (size_t)(l_pre * 5 + b) * NMODV;
;             bf16* hr = H + (size_t)row * DM;
; #pragma unroll
;             for (int j = 0; j < 8; ++j) { const int c = 4 * lane + 256 * j; const f32x4 g4 = *(const f32x4*)(gp + c), sh = *(const f32x4*)(mb + shift_idx * DM + c), scl = *(const f32x4*)(mb + scale_idx * DM + c);
	v_add_f32_e32 v14, v132, v153
	ds_bpermute_b32 v20, v131, v14
	s_waitcnt lgkmcnt(2)
	v_pk_add_f32 v[6:7], v[6:7], v[12:13]
	ds_bpermute_b32 v13, v130, v7
	ds_bpermute_b32 v12, v130, v6
	s_waitcnt lgkmcnt(3)
	v_add_f32_e32 v2, v2, v152
	s_waitcnt lgkmcnt(2)
	v_add_f32_e32 v14, v14, v20
	ds_bpermute_b32 v15, v130, v2
	ds_bpermute_b32 v20, v135, v14
	s_waitcnt lgkmcnt(2)
	v_pk_add_f32 v[6:7], v[6:7], v[12:13]
	ds_bpermute_b32 v13, v131, v7
	ds_bpermute_b32 v12, v131, v6
	s_waitcnt lgkmcnt(3)
	v_add_f32_e32 v2, v2, v15
	s_waitcnt lgkmcnt(2)
	v_add_f32_e32 v14, v14, v20
	ds_bpermute_b32 v15, v131, v2
	ds_bpermute_b32 v20, v136, v14
	s_waitcnt lgkmcnt(2)
	v_pk_add_f32 v[6:7], v[6:7], v[12:13]
	ds_bpermute_b32 v13, v135, v7
	ds_bpermute_b32 v12, v135, v6
	s_waitcnt lgkmcnt(3)
	v_add_f32_e32 v2, v2, v15
	s_waitcnt lgkmcnt(2)
	v_add_f32_e32 v14, v14, v20
	ds_bpermute_b32 v15, v135, v2
	ds_bpermute_b32 v20, v137, v14
	s_waitcnt lgkmcnt(2)
	v_pk_add_f32 v[6:7], v[6:7], v[12:13]
	ds_bpermute_b32 v13, v136, v7
	ds_bpermute_b32 v12, v136, v6
	s_waitcnt lgkmcnt(3)
	v_add_f32_e32 v2, v2, v15
	ds_bpermute_b32 v15, v136, v2
	s_waitcnt lgkmcnt(1)
	v_pk_add_f32 v[78:79], v[6:7], v[12:13]
	v_add_f32_e32 v6, v14, v20
	v_fmamk_f32 v6, v6, 0x3a000000, v169
	v_mul_f32_e32 v7, 0x4b800000, v6
	v_cmp_gt_f32_e32 vcc, s3, v6
	s_waitcnt lgkmcnt(0)
	v_add_f32_e32 v2, v2, v15
	ds_bpermute_b32 v82, v137, v2
	v_cndmask_b32_e32 v6, v6, v7, vcc
	v_rsq_f32_e32 v6, v6
	ds_bpermute_b32 v81, v137, v79
	ds_bpermute_b32 v80, v137, v78
	v_mul_f32_e32 v7, 0x45800000, v6
	v_cndmask_b32_e32 v6, v6, v7, vcc
	v_mul_f32_e32 v132, 0.5, v6
	v_pk_fma_f32 v[6:7], v[4:5], v[132:133], v[42:43] op_sel_hi:[1,0,1]
	v_pk_fma_f32 v[4:5], v[10:11], v[132:133], v[40:41] op_sel_hi:[1,0,1]
	v_pk_fma_f32 v[10:11], v[8:9], v[132:133], v[46:47] op_sel_hi:[1,0,1]
	v_pk_fma_f32 v[8:9], v[68:69], v[132:133], v[44:45] op_sel_hi:[1,0,1]
	v_pk_fma_f32 v[14:15], v[16:17], v[132:133], v[38:39] op_sel_hi:[1,0,1]
	v_pk_fma_f32 v[12:13], v[18:19], v[132:133], v[36:37] op_sel_hi:[1,0,1]
	v_pk_fma_f32 v[22:23], v[70:71], v[132:133], v[54:55] op_sel_hi:[1,0,1]
	v_pk_fma_f32 v[20:21], v[72:73], v[132:133], v[52:53] op_sel_hi:[1,0,1]
	v_pk_fma_f32 v[18:19], v[74:75], v[132:133], v[50:51] op_sel_hi:[1,0,1]
	v_pk_fma_f32 v[16:17], v[76:77], v[132:133], v[48:49] op_sel_hi:[1,0,1]
	v_pk_fma_f32 v[26:27], v[26:27], v[132:133], v[58:59] op_sel_hi:[1,0,1]
	v_pk_fma_f32 v[24:25], v[24:25], v[132:133], v[56:57] op_sel_hi:[1,0,1]
	v_pk_fma_f32 v[30:31], v[28:29], v[132:133], v[62:63] op_sel_hi:[1,0,1]
	v_pk_fma_f32 v[28:29], v[156:157], v[132:133], v[60:61] op_sel_hi:[1,0,1]
	v_pk_fma_f32 v[34:35], v[34:35], v[132:133], v[66:67] op_sel_hi:[1,0,1]
	v_pk_fma_f32 v[32:33], v[32:33], v[132:133], v[64:65] op_sel_hi:[1,0,1]
	s_and_b64 vcc, exec, s[6:7]
	s_cbranch_vccz .LBB0_27
	s_mov_b64 s[14:15], 0x14e00000
	v_lshl_add_u64 v[36:37], v[120:121], 0, s[14:15]
	s_mov_b64 s[14:15], 0x14e00400
	v_lshl_add_u64 v[38:39], v[120:121], 0, s[14:15]
	s_mov_b64 s[14:15], 0x14e00800
	v_lshl_add_u64 v[40:41], v[120:121], 0, s[14:15]
	s_mov_b64 s[14:15], 0x14e00c00
	v_pk_mul_f32 v[52:53], v[132:133], v[132:133] op_sel_hi:[0,1]
	s_waitcnt lgkmcnt(0)
	v_pk_add_f32 v[54:55], v[78:79], v[80:81]
	v_lshl_add_u64 v[42:43], v[120:121], 0, s[14:15]
	s_mov_b64 s[14:15], 0x14e01000
	v_add_f32_e32 v2, v2, v82
	v_pk_mul_f32 v[52:53], v[54:55], v[52:53]
	v_lshl_add_u64 v[44:45], v[120:121], 0, s[14:15]
	s_mov_b64 s[14:15], 0x14e01400
	v_add_f32_e32 v2, v2, v53
	v_lshl_add_u64 v[46:47], v[120:121], 0, s[14:15]
	s_mov_b64 s[14:15], 0x14e01800
	v_add_f32_e32 v2, v52, v2
	v_lshl_add_u64 v[48:49], v[120:121], 0, s[14:15]
	s_mov_b64 s[14:15], 0x14e01c00
	v_fmamk_f32 v2, v2, 0x3a000000, v169
	v_lshl_add_u64 v[50:51], v[120:121], 0, s[14:15]
	global_store_dwordx4 v[36:37], v[4:7], off
	global_store_dwordx4 v[38:39], v[8:11], off
	global_store_dwordx4 v[40:41], v[12:15], off
	global_store_dwordx4 v[42:43], v[20:23], off
	global_store_dwordx4 v[44:45], v[16:19], off
	global_store_dwordx4 v[46:47], v[24:27], off
	global_store_dwordx4 v[48:49], v[28:31], off
	global_store_dwordx4 v[50:51], v[32:35], off
	v_cmp_gt_f32_e32 vcc, s3, v2
	v_mul_f32_e32 v36, 0x4b800000, v2
	s_add_i32 s5, s5, 5
	v_cndmask_b32_e32 v2, v2, v36, vcc
	v_rsq_f32_e32 v2, v2
	s_mul_hi_i32 s9, s5, 0x12000
	s_mul_i32 s5, s5, 0x12000
	s_add_u32 s16, s18, s5
	s_addc_u32 s17, s19, s9
	v_mul_f32_e32 v36, 0x45800000, v2
	s_add_u32 s14, s16, 0x2000
	v_cndmask_b32_e32 v2, v2, v36, vcc
	s_addc_u32 s15, s17, 0
	global_load_dwordx4 v[36:39], v[104:105], off
	global_load_dwordx4 v[40:43], v145, s[16:17]
	global_load_dwordx4 v[44:47], v145, s[14:15]
	v_pk_mul_f32 v[50:51], v[4:5], v[2:3] op_sel_hi:[1,0]
	v_pk_mul_f32 v[48:49], v[6:7], v[2:3] op_sel_hi:[1,0]
	s_mov_b32 s3, 0x19600000
	v_pk_mul_f32 v[52:53], v[8:9], v[2:3] op_sel_hi:[1,0]
	s_waitcnt vmcnt(2)
	v_pk_mul_f32 v[36:37], v[50:51], v[36:37]
	v_pk_mul_f32 v[38:39], v[48:49], v[38:39]
	s_waitcnt vmcnt(0)
; __device__ __forceinline__ unsigned pk2(float lo, float hi) { return f2bf(lo) | (f2bf(hi) << 16); }
; __device__ __forceinline__ void rowwise_phase(const Params& P, int mrows, bool first, int l_post, int j_post, int gate_idx, float coef, bool final_, int l_pre, int j_pre, int shift_idx, int scale_idx) {
;     ...
; #pragma unroll
;             for (int j = 0; j < 8; ++j) { const int c = 4 * lane + 256 * j; const f32x4 g4 = *(const f32x4*)(gp + c), sh = *(const f32x4*)(mb + shift_idx * DM + c), scl = *(const f32x4*)(mb + scale_idx * DM + c);
;                 const f32x4 h = (xv[j] * rs) * g4 * (scl + 1.f) + sh; u32x2 w; w.x = pk2(h.x, h.y); w.y = pk2(h.z, h.w); *(u32x2*)(hr + c) = w; }
	v_pk_add_f32 v[44:45], v[44:45], 1.0 op_sel_hi:[1,0]
	v_pk_add_f32 v[46:47], v[46:47], 1.0 op_sel_hi:[1,0]
	v_pk_fma_f32 v[36:37], v[36:37], v[44:45], v[40:41]
	v_pk_fma_f32 v[38:39], v[38:39], v[46:47], v[42:43]
	v_bfe_u32 v40, v36, 16, 1
	v_add3_u32 v36, v36, v40, s71
	v_bfe_u32 v40, v37, 16, 1
	v_lshrrev_b32_e32 v36, 16, v36
	v_add3_u32 v37, v37, v40, s71
	v_and_or_b32 v40, v37, s70, v36
	v_bfe_u32 v36, v38, 16, 1
	v_add3_u32 v36, v38, v36, s71
	v_bfe_u32 v37, v39, 16, 1
	v_lshrrev_b32_e32 v36, 16, v36
	v_add3_u32 v37, v39, v37, s71
	v_and_or_b32 v41, v37, s70, v36
	v_add_co_u32_e32 v36, vcc, s3, v118
	v_pk_mul_f32 v[50:51], v[10:11], v[2:3] op_sel_hi:[1,0]
	s_nop 0
	v_addc_co_u32_e32 v37, vcc, 0, v119, vcc
	global_store_dwordx2 v[36:37], v[40:41], off
	global_load_dwordx4 v[196:199], v[104:105], off offset:1024
	global_load_dwordx4 v[200:203], v145, s[16:17] offset:1024
	global_load_dwordx4 v[204:207], v142, s[14:15]
	global_load_dwordx4 v[208:211], v[104:105], off offset:2048
	global_load_dwordx4 v[212:215], v145, s[16:17] offset:2048
	global_load_dwordx4 v[216:219], v143, s[14:15]
	global_load_dwordx4 v[220:223], v[104:105], off offset:3072
	global_load_dwordx4 v[224:227], v145, s[16:17] offset:3072
	global_load_dwordx4 v[228:231], v144, s[14:15]
	global_load_dwordx4 v[232:235], v[106:107], off
	global_load_dwordx4 v[236:239], v138, s[16:17]
	global_load_dwordx4 v[240:243], v138, s[14:15]
	s_nop 0
	s_waitcnt vmcnt(11)
	v_pk_mul_f32 v[38:39], v[52:53], v[196:197]
	v_pk_mul_f32 v[40:41], v[50:51], v[198:199]
	s_waitcnt vmcnt(9)
	v_pk_add_f32 v[46:47], v[204:205], 1.0 op_sel_hi:[1,0]
	v_pk_add_f32 v[48:49], v[206:207], 1.0 op_sel_hi:[1,0]
	v_pk_fma_f32 v[38:39], v[38:39], v[46:47], v[200:201]
	v_pk_fma_f32 v[40:41], v[40:41], v[48:49], v[202:203]
	v_bfe_u32 v42, v38, 16, 1
	v_add3_u32 v38, v38, v42, s71
	v_bfe_u32 v42, v39, 16, 1
	v_lshrrev_b32_e32 v38, 16, v38
	v_add3_u32 v39, v39, v42, s71
	v_and_or_b32 v38, v39, s70, v38
	v_bfe_u32 v39, v40, 16, 1
	v_add3_u32 v39, v40, v39, s71
	v_bfe_u32 v40, v41, 16, 1
	v_lshrrev_b32_e32 v39, 16, v39
	v_add3_u32 v40, v41, v40, s71
	v_and_or_b32 v39, v40, s70, v39
	global_store_dwordx2 v[36:37], v[38:39], off offset:512
	global_load_dwordx4 v[196:199], v[108:109], off
	global_load_dwordx4 v[200:203], v139, s[16:17]
	global_load_dwordx4 v[204:207], v139, s[14:15]
	s_nop 0
	v_pk_mul_f32 v[52:53], v[12:13], v[2:3] op_sel_hi:[1,0]
	v_pk_mul_f32 v[50:51], v[14:15], v[2:3] op_sel_hi:[1,0]
	s_waitcnt vmcnt(12)
	v_pk_mul_f32 v[38:39], v[52:53], v[208:209]
	v_pk_mul_f32 v[40:41], v[50:51], v[210:211]
	s_waitcnt vmcnt(10)
	v_pk_add_f32 v[46:47], v[216:217], 1.0 op_sel_hi:[1,0]
	v_pk_add_f32 v[48:49], v[218:219], 1.0 op_sel_hi:[1,0]
	v_pk_fma_f32 v[38:39], v[38:39], v[46:47], v[212:213]
	v_pk_fma_f32 v[40:41], v[40:41], v[48:49], v[214:215]
	v_bfe_u32 v42, v38, 16, 1
	v_add3_u32 v38, v38, v42, s71
	v_bfe_u32 v42, v39, 16, 1
	v_lshrrev_b32_e32 v38, 16, v38
	v_add3_u32 v39, v39, v42, s71
	v_and_or_b32 v38, v39, s70, v38
	v_bfe_u32 v39, v40, 16, 1
	v_add3_u32 v39, v40, v39, s71
	v_bfe_u32 v40, v41, 16, 1
	v_lshrrev_b32_e32 v39, 16, v39
	v_add3_u32 v40, v41, v40, s71
	v_and_or_b32 v39, v40, s70, v39
	global_store_dwordx2 v[36:37], v[38:39], off offset:1024
	global_load_dwordx4 v[208:211], v[110:111], off
	global_load_dwordx4 v[212:215], v140, s[16:17]
	global_load_dwordx4 v[216:219], v140, s[14:15]
	s_nop 0
	v_pk_mul_f32 v[52:53], v[20:21], v[2:3] op_sel_hi:[1,0]
	v_pk_mul_f32 v[50:51], v[22:23], v[2:3] op_sel_hi:[1,0]
	s_waitcnt vmcnt(13)
	v_pk_mul_f32 v[38:39], v[52:53], v[220:221]
	v_pk_mul_f32 v[40:41], v[50:51], v[222:223]
	s_waitcnt vmcnt(11)
; __device__ __forceinline__ unsigned pk2(float lo, float hi) { return f2bf(lo) | (f2bf(hi) << 16); }
; __device__ __forceinline__ void rowwise_phase(const Params& P, int mrows, bool first, int l_post, int j_post, int gate_idx, float coef, bool final_, int l_pre, int j_pre, int shift_idx, int scale_idx) {
;     ...
; #pragma unroll
;             for (int j = 0; j < 8; ++j) { const int c = 4 * lane + 256 * j; const f32x4 g4 = *(const f32x4*)(gp + c), sh = *(const f32x4*)(mb + shift_idx * DM + c), scl = *(const f32x4*)(mb + scale_idx * DM + c);
;                 const f32x4 h = (xv[j] * rs) * g4 * (scl + 1.f) + sh; u32x2 w; w.x = pk2(h.x, h.y); w.y = pk2(h.z, h.w); *(u32x2*)(hr + c) = w; }
	v_pk_add_f32 v[46:47], v[228:229], 1.0 op_sel_hi:[1,0]
	v_pk_add_f32 v[48:49], v[230:231], 1.0 op_sel_hi:[1,0]
	v_pk_fma_f32 v[38:39], v[38:39], v[46:47], v[224:225]
	v_pk_fma_f32 v[40:41], v[40:41], v[48:49], v[226:227]
	v_bfe_u32 v42, v38, 16, 1
	v_add3_u32 v38, v38, v42, s71
	v_bfe_u32 v42, v39, 16, 1
	v_lshrrev_b32_e32 v38, 16, v38
	v_add3_u32 v39, v39, v42, s71
	v_and_or_b32 v38, v39, s70, v38
	v_bfe_u32 v39, v40, 16, 1
	v_add3_u32 v39, v40, v39, s71
	v_bfe_u32 v40, v41, 16, 1
	v_lshrrev_b32_e32 v39, 16, v39
	v_add3_u32 v40, v41, v40, s71
	v_and_or_b32 v39, v40, s70, v39
	global_store_dwordx2 v[36:37], v[38:39], off offset:1536
	global_load_dwordx4 v[220:223], v[112:113], off
	global_load_dwordx4 v[224:227], v141, s[16:17]
	global_load_dwordx4 v[228:231], v141, s[14:15]
	s_nop 0
	v_pk_mul_f32 v[52:53], v[16:17], v[2:3] op_sel_hi:[1,0]
	v_pk_mul_f32 v[50:51], v[18:19], v[2:3] op_sel_hi:[1,0]
	s_waitcnt vmcnt(14)
	v_pk_mul_f32 v[38:39], v[52:53], v[232:233]
	v_pk_mul_f32 v[40:41], v[50:51], v[234:235]
	s_waitcnt vmcnt(12)
	v_pk_add_f32 v[46:47], v[240:241], 1.0 op_sel_hi:[1,0]
	v_pk_add_f32 v[48:49], v[242:243], 1.0 op_sel_hi:[1,0]
	v_pk_fma_f32 v[38:39], v[38:39], v[46:47], v[236:237]
	v_pk_fma_f32 v[40:41], v[40:41], v[48:49], v[238:239]
	v_bfe_u32 v42, v38, 16, 1
	v_add3_u32 v38, v38, v42, s71
	v_bfe_u32 v42, v39, 16, 1
	v_lshrrev_b32_e32 v38, 16, v38
	v_add3_u32 v39, v39, v42, s71
	v_and_or_b32 v38, v39, s70, v38
	v_bfe_u32 v39, v40, 16, 1
	v_add3_u32 v39, v40, v39, s71
	v_bfe_u32 v40, v41, 16, 1
	v_lshrrev_b32_e32 v39, 16, v39
	v_add3_u32 v40, v41, v40, s71
	v_and_or_b32 v39, v40, s70, v39
	global_store_dwordx2 v[36:37], v[38:39], off offset:2048
	s_nop 0
	v_pk_mul_f32 v[52:53], v[24:25], v[2:3] op_sel_hi:[1,0]
	v_pk_mul_f32 v[50:51], v[26:27], v[2:3] op_sel_hi:[1,0]
	s_waitcnt vmcnt(11)
	v_pk_mul_f32 v[38:39], v[52:53], v[196:197]
	v_pk_mul_f32 v[40:41], v[50:51], v[198:199]
	s_waitcnt vmcnt(9)
	v_pk_add_f32 v[46:47], v[204:205], 1.0 op_sel_hi:[1,0]
	v_pk_add_f32 v[48:49], v[206:207], 1.0 op_sel_hi:[1,0]
	v_pk_fma_f32 v[38:39], v[38:39], v[46:47], v[200:201]
	v_pk_fma_f32 v[40:41], v[40:41], v[48:49], v[202:203]
	v_bfe_u32 v42, v38, 16, 1
	v_add3_u32 v38, v38, v42, s71
	v_bfe_u32 v42, v39, 16, 1
	v_lshrrev_b32_e32 v38, 16, v38
	v_add3_u32 v39, v39, v42, s71
	v_and_or_b32 v38, v39, s70, v38
	v_bfe_u32 v39, v40, 16, 1
	v_add3_u32 v39, v40, v39, s71
	v_bfe_u32 v40, v41, 16, 1
	v_lshrrev_b32_e32 v39, 16, v39
	v_add3_u32 v40, v41, v40, s71
	v_and_or_b32 v39, v40, s70, v39
	global_store_dwordx2 v[36:37], v[38:39], off offset:2560
	s_nop 0
	v_pk_mul_f32 v[52:53], v[28:29], v[2:3] op_sel_hi:[1,0]
	v_pk_mul_f32 v[50:51], v[30:31], v[2:3] op_sel_hi:[1,0]
	s_waitcnt vmcnt(8)
	v_pk_mul_f32 v[38:39], v[52:53], v[208:209]
	v_pk_mul_f32 v[40:41], v[50:51], v[210:211]
	s_waitcnt vmcnt(6)
	v_pk_add_f32 v[46:47], v[216:217], 1.0 op_sel_hi:[1,0]
	v_pk_add_f32 v[48:49], v[218:219], 1.0 op_sel_hi:[1,0]
	v_pk_fma_f32 v[38:39], v[38:39], v[46:47], v[212:213]
	v_pk_fma_f32 v[40:41], v[40:41], v[48:49], v[214:215]
	v_bfe_u32 v42, v38, 16, 1
	v_add3_u32 v38, v38, v42, s71
	v_bfe_u32 v42, v39, 16, 1
	v_lshrrev_b32_e32 v38, 16, v38
	v_add3_u32 v39, v39, v42, s71
	v_and_or_b32 v38, v39, s70, v38
	v_bfe_u32 v39, v40, 16, 1
	v_add3_u32 v39, v40, v39, s71
	v_bfe_u32 v40, v41, 16, 1
	v_lshrrev_b32_e32 v39, 16, v39
	v_add3_u32 v40, v41, v40, s71
	v_and_or_b32 v39, v40, s70, v39
	global_store_dwordx2 v[36:37], v[38:39], off offset:3072
	s_nop 0
	v_pk_mul_f32 v[52:53], v[2:3], v[32:33] op_sel_hi:[0,1]
	v_pk_mul_f32 v[50:51], v[2:3], v[34:35] op_sel_hi:[0,1]
	s_mov_b64 s[14:15], 0
	s_waitcnt vmcnt(5)
	v_pk_mul_f32 v[38:39], v[52:53], v[220:221]
	v_pk_mul_f32 v[40:41], v[50:51], v[222:223]
	s_waitcnt vmcnt(3)
	v_pk_add_f32 v[46:47], v[228:229], 1.0 op_sel_hi:[1,0]
	v_pk_add_f32 v[48:49], v[230:231], 1.0 op_sel_hi:[1,0]
	v_pk_fma_f32 v[38:39], v[38:39], v[46:47], v[224:225]
	v_pk_fma_f32 v[40:41], v[40:41], v[48:49], v[226:227]
	v_bfe_u32 v2, v38, 16, 1
	v_add3_u32 v2, v38, v2, s71
	v_bfe_u32 v38, v39, 16, 1
	v_lshrrev_b32_e32 v2, 16, v2
	v_add3_u32 v38, v39, v38, s71
	v_and_or_b32 v38, v38, s70, v2
	v_bfe_u32 v2, v40, 16, 1
	v_add3_u32 v2, v40, v2, s71
	v_bfe_u32 v39, v41, 16, 1
	v_lshrrev_b32_e32 v2, 16, v2
	v_add3_u32 v39, v41, v39, s71
	v_and_or_b32 v39, v39, s70, v2
	global_store_dwordx2 v[36:37], v[38:39], off offset:3584

; __device__ __forceinline__ float dot4(f32x4 a) { return (a.x * a.x + a.y * a.y) + (a.z * a.z + a.w * a.w); }
; __device__ __forceinline__ void rowwise_phase(const Params& P, int mrows, bool first, int l_post, int j_post, int gate_idx, float coef, bool final_, int l_pre, int j_pre, int shift_idx, int scale_idx) {
;     ...
;             const float* gp = P.norm_post + (size_t)(l_post * 3 + j_post) * DM; const float* mg = MOD + (size_t)(l_post * 5 + b) * NMODV + gate_idx * DM;
;             float sxx = 0.f, sxt = 0.f, stt = 0.f;
; #pragma unroll
;             for (int j = 0; j < 8; ++j) { const int c = 4 * lane + 256 * j; xv[j] = *(const f32x4*)(xr + c); const f32x4 g4 = *(const f32x4*)(gp + c), m4 = *(const f32x4*)(mg + c);
;                 ss += dot4(yv[j]); yv[j] = yv[j] * g4 * m4; sxx += dot4(xv[j]); stt += dot4(yv[j]);
;                 const f32x4 xt = xv[j] * yv[j]; sxt += (xt.x + xt.y) + (xt.z + xt.w); }
.LBB0_36:
	v_lshl_add_u64 v[36:37], s[94:95], 0, v[110:111]
	s_mov_b32 s1, 0x14e00000
	v_add_co_u32_e32 v116, vcc, s1, v36
	s_mov_b32 s1, 0x14e01000
	s_nop 0
	v_addc_co_u32_e32 v117, vcc, 0, v37, vcc
	global_load_dwordx4 v[56:59], v[0:1], off
	v_add_co_u32_e32 v114, vcc, s1, v36
	s_min_i32 s1, s0, 0x2000
	v_readlane_b32 s10, v255, 14
	v_addc_co_u32_e32 v115, vcc, 0, v37, vcc
	s_ashr_i32 s1, s1, 11
	s_mul_i32 s5, s10, 5
	global_load_dwordx4 v[60:63], v[0:1], off offset:1024
	global_load_dwordx4 v[64:67], v[0:1], off offset:2048
	global_load_dwordx4 v[40:43], v[114:115], off offset:-4096
	global_load_dwordx4 v[36:39], v[116:117], off offset:1024
	s_add_i32 s5, s1, s5
	s_mul_hi_i32 s1, s5, 0x12000
	s_mul_i32 s5, s5, 0x12000
	v_readlane_b32 s11, v255, 15
	s_add_u32 s10, s18, s5
	s_addc_u32 s11, s19, s1
	s_nop 2
	global_load_dwordx4 v[76:79], v128, s[10:11]
	global_load_dwordx4 v[72:75], v128, s[10:11] offset:1024
	global_load_dwordx4 v[68:71], v128, s[10:11] offset:2048
	global_load_dwordx4 v[44:47], v[116:117], off offset:2048
	global_load_dwordx4 v[80:83], v[0:1], off offset:3072
	global_load_dwordx4 v[84:87], v[88:89], off
	s_waitcnt vmcnt(0)
	v_pk_mul_f32 v[48:49], v[18:19], v[18:19]
	v_pk_mul_f32 v[50:51], v[16:17], v[16:17]
	v_mov_b32_e32 v119, v4
	v_pk_mov_b32 v[52:53], v[50:51], v[48:49] op_sel:[1,0]
	v_mov_b32_e32 v51, v49
	v_pk_add_f32 v[52:53], v[52:53], v[50:51]
	global_load_dwordx4 v[48:51], v[114:115], off
	v_pk_add_f32 v[152:153], v[52:53], v[52:53] op_sel_hi:[0,1]
	global_load_dwordx4 v[52:55], v[116:117], off offset:3072
	global_load_dwordx4 v[140:143], v128, s[10:11] offset:3072
	global_load_dwordx4 v[144:147], v129, s[10:11]
	global_load_dwordx4 v[148:151], v135, s[10:11]
	v_mov_b32_e32 v121, v6
	v_mov_b32_e32 v118, v8
	v_mov_b32_e32 v120, v10
	v_mul_f32_e32 v152, v22, v22
	s_mov_b32 s3, 0x800000
	s_add_u32 s5, s16, s5
	s_addc_u32 s1, s17, s1
	v_lshl_add_u64 v[108:109], v[108:109], 0, s[6:7]
	v_lshl_add_u64 v[110:111], v[110:111], 0, s[8:9]
	s_waitcnt vmcnt(15)
	v_pk_mul_f32 v[58:59], v[6:7], v[58:59]
	v_pk_mul_f32 v[56:57], v[4:5], v[56:57]
	v_mov_b32_e32 v4, v9
	v_mov_b32_e32 v6, v11
	v_pk_mul_f32 v[4:5], v[4:5], v[4:5]
	v_pk_mul_f32 v[6:7], v[6:7], v[6:7]
	v_pk_fma_f32 v[4:5], v[118:119], v[118:119], v[4:5]
	v_pk_fma_f32 v[6:7], v[120:121], v[120:121], v[6:7]
	s_waitcnt vmcnt(14)
	v_pk_mul_f32 v[10:11], v[10:11], v[62:63]
	v_pk_mul_f32 v[8:9], v[8:9], v[60:61]
	s_waitcnt vmcnt(13)
	v_pk_mul_f32 v[60:61], v[18:19], v[66:67]
	v_pk_mul_f32 v[62:63], v[16:17], v[64:65]
	s_waitcnt vmcnt(12)
	v_mov_b32_e32 v18, v41
	s_waitcnt vmcnt(11)
	v_mov_b32_e32 v19, v37
	v_mov_b32_e32 v64, v42
	v_mov_b32_e32 v65, v38
	v_mov_b32_e32 v16, v40
	v_mov_b32_e32 v17, v36
	v_mov_b32_e32 v66, v43
	v_mov_b32_e32 v67, v39
	v_pk_add_f32 v[4:5], v[4:5], v[6:7]
	v_pk_mul_f32 v[6:7], v[18:19], v[18:19]
	v_pk_mul_f32 v[18:19], v[64:65], v[64:65]
	v_pk_add_f32 v[64:65], v[4:5], v[4:5] op_sel_hi:[0,1]
	v_pk_fma_f32 v[4:5], v[16:17], v[16:17], v[6:7]
	v_pk_fma_f32 v[6:7], v[66:67], v[66:67], v[18:19]
	s_waitcnt vmcnt(10)
	v_pk_mul_f32 v[16:17], v[78:79], v[58:59]
	v_pk_mul_f32 v[18:19], v[76:77], v[56:57]
	s_waitcnt vmcnt(9)
	v_pk_mul_f32 v[56:57], v[74:75], v[10:11]
	v_pk_mul_f32 v[58:59], v[72:73], v[8:9]
	v_mul_f32_e32 v2, v17, v17
	v_pk_mul_f32 v[8:9], v[42:43], v[16:17]
	v_pk_mul_f32 v[10:11], v[40:41], v[18:19]
	v_pk_mul_f32 v[74:75], v[38:39], v[56:57]
	v_pk_mul_f32 v[76:77], v[36:37], v[58:59]
	v_pk_add_f32 v[154:155], v[4:5], v[6:7]
	s_waitcnt vmcnt(8)
	v_pk_mul_f32 v[60:61], v[70:71], v[60:61]
	v_pk_mul_f32 v[62:63], v[68:69], v[62:63]
	v_mul_f32_e32 v4, v18, v18
	v_mul_f32_e32 v6, v19, v19
	v_mul_f32_e32 v66, v58, v58
	v_mul_f32_e32 v68, v59, v59
	v_mul_f32_e32 v70, v56, v56
	v_mul_f32_e32 v72, v57, v57
	v_pk_fma_f32 v[78:79], v[16:17], v[16:17], v[2:3] op_sel_hi:[1,1,0]
	v_add_f32_e32 v5, v10, v11
	v_add_f32_e32 v7, v8, v9
	s_waitcnt vmcnt(7)
	v_pk_mul_f32 v[8:9], v[46:47], v[46:47]
	v_pk_mul_f32 v[10:11], v[44:45], v[44:45]
	v_mov_b32_e32 v67, v76
	v_mov_b32_e32 v69, v77
	v_mov_b32_e32 v71, v74
	v_mov_b32_e32 v73, v75
	v_pk_mov_b32 v[118:119], v[10:11], v[8:9] op_sel:[1,0]
	v_mov_b32_e32 v11, v9
	v_pk_mul_f32 v[158:159], v[46:47], v[60:61]
	v_pk_mul_f32 v[160:161], v[44:45], v[62:63]
	v_pk_add_f32 v[4:5], v[4:5], v[6:7]
	v_mov_b32_e32 v79, v3
	v_pk_add_f32 v[6:7], v[66:67], v[68:69]
	v_pk_add_f32 v[66:67], v[70:71], v[72:73]
	v_pk_add_f32 v[156:157], v[10:11], v[118:119]
	v_mul_f32_e32 v8, v62, v62
	v_mul_f32_e32 v10, v63, v63
	v_mul_f32_e32 v118, v60, v60
	v_mul_f32_e32 v120, v61, v61
	v_pk_add_f32 v[4:5], v[4:5], v[78:79]
	v_pk_add_f32 v[6:7], v[6:7], v[66:67]
	v_mov_b32_e32 v9, v160
	v_mov_b32_e32 v11, v161
	v_mov_b32_e32 v119, v158
	global_load_dwordx4 v[68:71], v[90:91], off
	global_load_dwordx4 v[76:79], v[92:93], off
	v_mov_b32_e32 v121, v159
	v_pk_add_f32 v[66:67], v[4:5], v[6:7]
	v_pk_add_f32 v[8:9], v[8:9], v[10:11]
	global_load_dwordx4 v[72:75], v130, s[10:11]
	v_pk_add_f32 v[10:11], v[118:119], v[120:121]
	global_load_dwordx4 v[4:7], v[114:115], off offset:1024
	v_pk_add_f32 v[8:9], v[8:9], v[10:11]
	v_mul_f32_e32 v2, v12, v12
	v_pk_add_f32 v[158:159], v[66:67], v[8:9]
	v_pk_fma_f32 v[8:9], v[12:13], v[12:13], v[2:3] op_sel_hi:[1,1,0]
	v_mul_f32_e32 v2, v14, v14
	v_pk_fma_f32 v[10:11], v[14:15], v[14:15], v[2:3] op_sel_hi:[1,1,0]
	s_waitcnt vmcnt(10)
	v_pk_mul_f32 v[14:15], v[14:15], v[82:83]
	v_pk_mul_f32 v[66:67], v[12:13], v[80:81]
	global_load_dwordx4 v[80:83], v131, s[10:11]
	s_waitcnt vmcnt(7)
; __device__ __forceinline__ float dot4(f32x4 a) { return (a.x * a.x + a.y * a.y) + (a.z * a.z + a.w * a.w); }
; __device__ __forceinline__ void rowwise_phase(const Params& P, int mrows, bool first, int l_post, int j_post, int gate_idx, float coef, bool final_, int l_pre, int j_pre, int shift_idx, int scale_idx) {
;     ...
;             for (int j = 0; j < 8; ++j) { const int c = 4 * lane + 256 * j; xv[j] = *(const f32x4*)(xr + c); const f32x4 g4 = *(const f32x4*)(gp + c), m4 = *(const f32x4*)(mg + c);
;                 ss += dot4(yv[j]); yv[j] = yv[j] * g4 * m4; sxx += dot4(xv[j]); stt += dot4(yv[j]);
;                 const f32x4 xt = xv[j] * yv[j]; sxt += (xt.x + xt.y) + (xt.z + xt.w); }
; #pragma unroll
;             for (int o = 1; o < 64; o <<= 1) { ss += __shfl_xor(ss, o); sxx += __shfl_xor(sxx, o); sxt += __shfl_xor(sxt, o); stt += __shfl_xor(stt, o); }
	v_pk_mul_f32 v[12:13], v[142:143], v[14:15]
	v_pk_mul_f32 v[14:15], v[140:141], v[66:67]
	v_pk_mul_f32 v[142:143], v[54:55], v[12:13]
	v_pk_mul_f32 v[160:161], v[52:53], v[14:15]
	v_mul_f32_e32 v66, v14, v14
	v_mul_f32_e32 v118, v15, v15
	v_mul_f32_e32 v120, v12, v12
	v_mul_f32_e32 v140, v13, v13
	v_mov_b32_e32 v67, v160
	v_mov_b32_e32 v119, v161
	v_mov_b32_e32 v121, v142
	v_mov_b32_e32 v141, v143
	v_pk_add_f32 v[66:67], v[66:67], v[118:119]
	v_pk_add_f32 v[118:119], v[120:121], v[140:141]
	v_mul_f32_e32 v8, v20, v20
	v_mul_f32_e32 v10, v21, v21
	v_mul_f32_e32 v64, v23, v23
	v_pk_add_f32 v[140:141], v[66:67], v[118:119]
	v_pk_add_f32 v[66:67], v[8:9], v[10:11]
	v_pk_add_f32 v[64:65], v[152:153], v[64:65]
	global_load_dwordx4 v[118:121], v[94:95], off
	v_pk_add_f32 v[64:65], v[66:67], v[64:65]
	v_pk_mul_f32 v[22:23], v[22:23], v[86:87]
	v_pk_mul_f32 v[20:21], v[20:21], v[84:85]
	v_pk_add_f32 v[142:143], v[64:65], v[64:65] op_sel_hi:[0,1]
	s_waitcnt vmcnt(7)
	v_pk_mul_f32 v[64:65], v[146:147], v[22:23]
	v_pk_mul_f32 v[66:67], v[144:145], v[20:21]
	global_load_dwordx4 v[20:23], v[114:115], off offset:3072
	global_load_dwordx4 v[8:11], v[114:115], off offset:2048
	v_mul_f32_e32 v2, v48, v48
	v_mul_f32_e32 v132, v49, v49
	v_pk_add_f32 v[84:85], v[154:155], v[154:155] op_sel:[0,1] op_sel_hi:[1,0]
	v_pk_add_f32 v[86:87], v[156:157], v[156:157] op_sel:[0,1] op_sel_hi:[1,0]
	v_mov_b32_e32 v85, v2
	v_mov_b32_e32 v87, v132
	v_mul_f32_e32 v2, v53, v53
	v_pk_add_f32 v[84:85], v[84:85], v[86:87]
	v_pk_fma_f32 v[86:87], v[52:53], v[52:53], v[2:3] op_sel_hi:[1,1,0]
	v_mul_f32_e32 v2, v55, v55
	v_mul_f32_e32 v139, v50, v50
	v_mul_f32_e32 v142, v51, v51
	v_pk_fma_f32 v[144:145], v[54:55], v[54:55], v[2:3] op_sel_hi:[1,1,0]
	v_mov_b32_e32 v87, v142
	v_mov_b32_e32 v145, v139
	v_pk_add_f32 v[86:87], v[86:87], v[144:145]
	v_pk_mul_f32 v[154:155], v[50:51], v[64:65]
	v_pk_mul_f32 v[156:157], v[48:49], v[66:67]
	v_pk_add_f32 v[84:85], v[84:85], v[86:87]
	v_mul_f32_e32 v86, v66, v66
	v_mul_f32_e32 v144, v67, v67
	v_mul_f32_e32 v146, v64, v64
	v_mul_f32_e32 v152, v65, v65
	v_mov_b32_e32 v87, v156
	v_mov_b32_e32 v145, v157
	v_mov_b32_e32 v147, v154
	v_mov_b32_e32 v153, v155
	v_pk_add_f32 v[86:87], v[86:87], v[144:145]
	v_pk_add_f32 v[144:145], v[146:147], v[152:153]
	v_pk_mul_f32 v[146:147], v[26:27], v[26:27]
	v_pk_mul_f32 v[152:153], v[24:25], v[24:25]
	v_mul_f32_e32 v2, v28, v28
	v_pk_mov_b32 v[154:155], v[152:153], v[146:147] op_sel:[1,0]
	v_mov_b32_e32 v153, v147
	s_waitcnt vmcnt(7)
	v_pk_mul_f32 v[26:27], v[26:27], v[70:71]
	v_pk_mul_f32 v[24:25], v[24:25], v[68:69]
	v_pk_add_f32 v[146:147], v[154:155], v[152:153]
	v_pk_fma_f32 v[164:165], v[28:29], v[28:29], v[2:3] op_sel_hi:[1,1,0]
	v_mul_f32_e32 v2, v30, v30
	s_waitcnt vmcnt(5)
	v_pk_mul_f32 v[68:69], v[74:75], v[26:27]
	v_pk_mul_f32 v[70:71], v[72:73], v[24:25]
	s_waitcnt vmcnt(4)
	v_pk_mul_f32 v[24:25], v[6:7], v[6:7]
	v_pk_mul_f32 v[26:27], v[4:5], v[4:5]
	v_pk_add_f32 v[146:147], v[146:147], v[146:147] op_sel_hi:[0,1]
	v_pk_mov_b32 v[72:73], v[26:27], v[24:25] op_sel:[1,0]
	v_mov_b32_e32 v27, v25
	v_pk_fma_f32 v[166:167], v[30:31], v[30:31], v[2:3] op_sel_hi:[1,1,0]
	v_pk_add_f32 v[72:73], v[26:27], v[72:73]
	v_pk_mul_f32 v[24:25], v[30:31], v[78:79]
	v_pk_mul_f32 v[26:27], v[28:29], v[76:77]
	v_mul_f32_e32 v164, v32, v32
	v_mul_f32_e32 v166, v33, v33
	v_mul_f32_e32 v146, v34, v34
	v_mul_f32_e32 v142, v35, v35
	s_waitcnt vmcnt(3)
	v_pk_mul_f32 v[76:77], v[82:83], v[24:25]
	v_pk_mul_f32 v[78:79], v[80:81], v[26:27]
	v_pk_add_f32 v[80:81], v[164:165], v[166:167]
	v_pk_add_f32 v[82:83], v[146:147], v[142:143]
	s_add_u32 s10, s5, 0xc000
	v_pk_add_f32 v[80:81], v[80:81], v[82:83]
	s_addc_u32 s11, s1, 0
	v_add_f32_e32 v2, v80, v81
	ds_bpermute_b32 v25, v122, v2
	v_pk_mul_f32 v[160:161], v[6:7], v[68:69]
	v_pk_mul_f32 v[162:163], v[4:5], v[70:71]
	s_add_u32 s12, s5, 0xe000
	s_addc_u32 s13, s1, 0
	s_waitcnt lgkmcnt(0)
	v_add_f32_e32 v2, v2, v25
	ds_bpermute_b32 v25, v123, v2
	v_mul_f32_e32 v74, v70, v70
	v_mul_f32_e32 v152, v71, v71
	s_waitcnt vmcnt(2)
	v_pk_mul_f32 v[32:33], v[32:33], v[118:119]
	v_pk_mul_f32 v[34:35], v[34:35], v[120:121]
	s_waitcnt lgkmcnt(0)
	v_add_f32_e32 v2, v2, v25
	ds_bpermute_b32 v25, v124, v2
	v_pk_mul_f32 v[120:121], v[148:149], v[32:33]
	v_pk_add_f32 v[32:33], v[84:85], v[84:85] op_sel:[0,1] op_sel_hi:[1,0]
	v_pk_mul_f32 v[118:119], v[150:151], v[34:35]
	s_waitcnt vmcnt(1)
	v_mul_f32_e32 v27, v20, v20
	s_waitcnt lgkmcnt(0)
	v_add_f32_e32 v25, v2, v25
	v_mov_b32_e32 v33, v27
	ds_bpermute_b32 v27, v125, v25
	s_waitcnt vmcnt(0)
	v_mul_f32_e32 v2, v9, v9
	v_pk_fma_f32 v[84:85], v[8:9], v[8:9], v[2:3] op_sel_hi:[1,1,0]
	v_mul_f32_e32 v2, v11, v11
	v_pk_fma_f32 v[142:143], v[10:11], v[10:11], v[2:3] op_sel_hi:[1,1,0]
	s_waitcnt lgkmcnt(0)
	v_add_f32_e32 v25, v25, v27
	ds_bpermute_b32 v27, v126, v25
	v_mul_f32_e32 v29, v21, v21
	v_pk_add_f32 v[34:35], v[72:73], v[72:73] op_sel:[0,1] op_sel_hi:[1,0]
	v_pk_mul_f32 v[80:81], v[10:11], v[76:77]
	v_mov_b32_e32 v35, v29
	s_waitcnt lgkmcnt(0)
	v_add_f32_e32 v2, v25, v27
	ds_bpermute_b32 v25, v127, v2
	v_pk_add_f32 v[72:73], v[32:33], v[34:35]
	v_pk_add_f32 v[32:33], v[158:159], v[140:141]
	v_pk_add_f32 v[34:35], v[86:87], v[144:145]
	v_pk_mul_f32 v[82:83], v[8:9], v[78:79]
	s_waitcnt lgkmcnt(0)
; __device__ __forceinline__ unsigned pk2(float lo, float hi) { return f2bf(lo) | (f2bf(hi) << 16); }
; __device__ __forceinline__ float dot4(f32x4 a) { return (a.x * a.x + a.y * a.y) + (a.z * a.z + a.w * a.w); }
; __device__ __forceinline__ void rowwise_phase(const Params& P, int mrows, bool first, int l_post, int j_post, int gate_idx, float coef, bool final_, int l_pre, int j_pre, int shift_idx, int scale_idx) {
;     ...
;             const float rs = rsqrtf(ss * (1.f / DM) + EPS) * coef;
;             ss_new = sxx + 2.f * rs * sxt + rs * rs * stt;
; #pragma unroll
;             for (int j = 0; j < 8; ++j) xv[j] += yv[j] * rs;
;         }
;         if (final_) {
;             float* o = P.out + (size_t)row * DM;
; #pragma unroll
;             for (int j = 0; j < 8; ++j) *(f32x4*)(o + 4 * lane + 256 * j) = xv[j];
;             continue;
;         }
;         {
;             float* xr = X + (size_t)row * DM; float ss = 0.f;
; #pragma unroll
;             for (int j = 0; j < 8; ++j) { if (!first) *(f32x4*)(xr + 4 * lane + 256 * j) = xv[j]; else ss += dot4(xv[j]); }
;             if (first) ss = wave_sum(ss); else ss = ss_new;
;             const float rs = rsqrtf(ss * (1.f / DM) + EPS);
;             const float* gp = P.norm_pre + (size_t)(l_pre * 3 + j_pre) * DM; const float* mb = MOD + (size_t)(l_pre * 5 + b) * NMODV;
;             bf16* hr = H + (size_t)row * DM;
; #pragma unroll
;             for (int j = 0; j < 8; ++j) { const int c = 4 * lane + 256 * j; const f32x4 g4 = *(const f32x4*)(gp + c), sh = *(const f32x4*)(mb + shift_idx * DM + c), scl = *(const f32x4*)(mb + scale_idx * DM + c);
;                 const f32x4 h = (xv[j] * rs) * g4 * (scl + 1.f) + sh; u32x2 w; w.x = pk2(h.x, h.y); w.y = pk2(h.z, h.w); *(u32x2*)(hr + c) = w; }
	v_add_f32_e32 v2, v2, v25
	v_fmamk_f32 v2, v2, 0x3a000000, v169
	v_mul_f32_e32 v25, 0x4b800000, v2
	v_cmp_gt_f32_e32 vcc, s3, v2
	v_pk_add_f32 v[86:87], v[32:33], v[34:35]
	v_mul_f32_e32 v31, v22, v22
	v_cndmask_b32_e32 v2, v2, v25, vcc
	v_rsq_f32_e32 v2, v2
	v_mul_f32_e32 v75, v23, v23
	v_pk_mul_f32 v[166:167], v[22:23], v[118:119]
	v_pk_mul_f32 v[194:195], v[20:21], v[120:121]
	v_mul_f32_e32 v25, 0x45800000, v2
	v_cndmask_b32_e32 v132, v2, v25, vcc
	v_pk_fma_f32 v[34:35], v[16:17], v[132:133], v[42:43] op_sel_hi:[1,0,1]
	v_pk_fma_f32 v[32:33], v[18:19], v[132:133], v[40:41] op_sel_hi:[1,0,1]
	v_pk_fma_f32 v[38:39], v[56:57], v[132:133], v[38:39] op_sel_hi:[1,0,1]
	v_pk_fma_f32 v[36:37], v[58:59], v[132:133], v[36:37] op_sel_hi:[1,0,1]
	v_pk_fma_f32 v[42:43], v[60:61], v[132:133], v[46:47] op_sel_hi:[1,0,1]
	v_pk_fma_f32 v[40:41], v[62:63], v[132:133], v[44:45] op_sel_hi:[1,0,1]
	v_pk_fma_f32 v[46:47], v[12:13], v[132:133], v[54:55] op_sel_hi:[1,0,1]
	v_pk_fma_f32 v[44:45], v[14:15], v[132:133], v[52:53] op_sel_hi:[1,0,1]
	v_pk_fma_f32 v[18:19], v[64:65], v[132:133], v[50:51] op_sel_hi:[1,0,1]
	v_pk_fma_f32 v[16:17], v[66:67], v[132:133], v[48:49] op_sel_hi:[1,0,1]
	v_pk_fma_f32 v[14:15], v[68:69], v[132:133], v[6:7] op_sel_hi:[1,0,1]
	v_pk_fma_f32 v[12:13], v[70:71], v[132:133], v[4:5] op_sel_hi:[1,0,1]
	v_pk_fma_f32 v[10:11], v[76:77], v[132:133], v[10:11] op_sel_hi:[1,0,1]
	v_pk_fma_f32 v[8:9], v[78:79], v[132:133], v[8:9] op_sel_hi:[1,0,1]
	v_pk_fma_f32 v[6:7], v[118:119], v[132:133], v[22:23] op_sel_hi:[1,0,1]
	v_pk_fma_f32 v[4:5], v[120:121], v[132:133], v[20:21] op_sel_hi:[1,0,1]
	global_store_dwordx4 v[114:115], v[32:35], off offset:-4096
	global_store_dwordx4 v[116:117], v[36:39], off offset:1024
	global_store_dwordx4 v[116:117], v[40:43], off offset:2048
	global_store_dwordx4 v[116:117], v[44:47], off offset:3072
	global_store_dwordx4 v[114:115], v[16:19], off
	global_store_dwordx4 v[114:115], v[12:15], off offset:1024
	global_store_dwordx4 v[114:115], v[8:11], off offset:2048
	global_store_dwordx4 v[114:115], v[4:7], off offset:3072
	global_load_dwordx4 v[20:23], v[96:97], off
	global_load_dwordx4 v[48:51], v128, s[10:11]
	global_load_dwordx4 v[52:55], v128, s[12:13]
	v_mul_f32_e32 v154, v68, v68
	v_mul_f32_e32 v156, v69, v69
	v_mov_b32_e32 v85, v75
	v_mov_b32_e32 v75, v162
	v_mov_b32_e32 v153, v163
	v_mov_b32_e32 v155, v160
	v_mov_b32_e32 v157, v161
	v_mul_f32_e32 v28, v78, v78
	v_mul_f32_e32 v30, v79, v79
	v_mul_f32_e32 v24, v76, v76
	v_mul_f32_e32 v26, v77, v77
	v_mov_b32_e32 v143, v31
	v_pk_add_f32 v[74:75], v[74:75], v[152:153]
	v_pk_add_f32 v[140:141], v[154:155], v[156:157]
	v_mov_b32_e32 v29, v82
	v_mov_b32_e32 v31, v83
	v_mov_b32_e32 v25, v80
	v_mov_b32_e32 v27, v81
	v_mul_f32_e32 v146, v120, v120
	v_mul_f32_e32 v148, v121, v121
	v_mul_f32_e32 v150, v118, v118
	v_mul_f32_e32 v164, v119, v119
	v_pk_add_f32 v[56:57], v[74:75], v[140:141]
	v_pk_add_f32 v[28:29], v[28:29], v[30:31]
	v_pk_add_f32 v[24:25], v[24:25], v[26:27]
	v_mov_b32_e32 v147, v194
	v_mov_b32_e32 v149, v195
	v_mov_b32_e32 v151, v166
	v_mov_b32_e32 v165, v167
	v_pk_add_f32 v[56:57], v[86:87], v[56:57]
	v_pk_add_f32 v[24:25], v[28:29], v[24:25]
	v_pk_add_f32 v[26:27], v[146:147], v[148:149]
	v_pk_add_f32 v[28:29], v[150:151], v[164:165]
	v_pk_add_f32 v[24:25], v[56:57], v[24:25]
	v_pk_add_f32 v[26:27], v[26:27], v[28:29]
	v_pk_add_f32 v[28:29], v[84:85], v[142:143]
	v_pk_add_f32 v[24:25], v[24:25], v[26:27]
	v_pk_add_f32 v[28:29], v[72:73], v[28:29]
	ds_bpermute_b32 v27, v122, v25
	ds_bpermute_b32 v26, v122, v24
	v_add_f32_e32 v2, v28, v29
	ds_bpermute_b32 v28, v122, v2
	s_mov_b32 s1, 0x19600000
	s_add_i32 s0, s0, s4
	s_waitcnt lgkmcnt(1)
	v_pk_add_f32 v[24:25], v[24:25], v[26:27]
	ds_bpermute_b32 v27, v123, v25
	ds_bpermute_b32 v26, v123, v24
	s_waitcnt lgkmcnt(2)
	v_add_f32_e32 v2, v2, v28
	ds_bpermute_b32 v28, v123, v2
	s_waitcnt lgkmcnt(1)
	v_pk_add_f32 v[24:25], v[24:25], v[26:27]
	ds_bpermute_b32 v27, v124, v25
	ds_bpermute_b32 v26, v124, v24
	s_waitcnt lgkmcnt(2)
	v_add_f32_e32 v2, v2, v28
	ds_bpermute_b32 v28, v124, v2
	s_waitcnt lgkmcnt(1)
	v_pk_add_f32 v[24:25], v[24:25], v[26:27]
	ds_bpermute_b32 v27, v125, v25
	ds_bpermute_b32 v26, v125, v24
	s_waitcnt lgkmcnt(2)
	v_add_f32_e32 v2, v2, v28
	ds_bpermute_b32 v28, v125, v2
	s_waitcnt lgkmcnt(1)
	v_pk_add_f32 v[24:25], v[24:25], v[26:27]
	ds_bpermute_b32 v27, v126, v25
	ds_bpermute_b32 v26, v126, v24
	s_waitcnt lgkmcnt(2)
	v_add_f32_e32 v2, v2, v28
	ds_bpermute_b32 v28, v126, v2
	s_waitcnt lgkmcnt(1)
	v_pk_add_f32 v[24:25], v[24:25], v[26:27]
	ds_bpermute_b32 v27, v127, v25
	ds_bpermute_b32 v26, v127, v24
	s_waitcnt lgkmcnt(2)
	v_add_f32_e32 v2, v2, v28
	ds_bpermute_b32 v28, v127, v2
	s_waitcnt lgkmcnt(1)
	v_pk_add_f32 v[24:25], v[24:25], v[26:27]
	v_pk_mul_f32 v[26:27], v[132:133], v[132:133] op_sel_hi:[0,1]
	v_pk_mul_f32 v[24:25], v[24:25], v[26:27]
	s_waitcnt lgkmcnt(0)
	v_add_f32_e32 v2, v2, v28
	v_add_f32_e32 v2, v2, v25
	v_add_f32_e32 v2, v24, v2
	v_fmamk_f32 v2, v2, 0x3a000000, v169
	v_mul_f32_e32 v24, 0x4b800000, v2
	v_cmp_gt_f32_e32 vcc, s3, v2
	s_nop 1
	v_cndmask_b32_e32 v2, v2, v24, vcc
	v_rsq_f32_e32 v2, v2
	s_nop 0
	v_mul_f32_e32 v24, 0x45800000, v2
	v_cndmask_b32_e32 v2, v2, v24, vcc
	v_pk_mul_f32 v[26:27], v[32:33], v[2:3] op_sel_hi:[1,0]
	v_pk_mul_f32 v[24:25], v[34:35], v[2:3] op_sel_hi:[1,0]
	s_waitcnt vmcnt(2)
	v_pk_mul_f32 v[20:21], v[20:21], v[26:27]
	s_waitcnt vmcnt(0)
; __device__ __forceinline__ unsigned pk2(float lo, float hi) { return f2bf(lo) | (f2bf(hi) << 16); }
; __device__ __forceinline__ void rowwise_phase(const Params& P, int mrows, bool first, int l_post, int j_post, int gate_idx, float coef, bool final_, int l_pre, int j_pre, int shift_idx, int scale_idx) {
;     ...
; #pragma unroll
;             for (int j = 0; j < 8; ++j) { const int c = 4 * lane + 256 * j; const f32x4 g4 = *(const f32x4*)(gp + c), sh = *(const f32x4*)(mb + shift_idx * DM + c), scl = *(const f32x4*)(mb + scale_idx * DM + c);
;                 const f32x4 h = (xv[j] * rs) * g4 * (scl + 1.f) + sh; u32x2 w; w.x = pk2(h.x, h.y); w.y = pk2(h.z, h.w); *(u32x2*)(hr + c) = w; }
	v_pk_add_f32 v[26:27], v[52:53], 1.0 op_sel_hi:[1,0]
	v_pk_mul_f32 v[22:23], v[22:23], v[24:25]
	v_pk_add_f32 v[24:25], v[54:55], 1.0 op_sel_hi:[1,0]
	v_pk_fma_f32 v[20:21], v[26:27], v[20:21], v[48:49]
	v_pk_fma_f32 v[22:23], v[24:25], v[22:23], v[50:51]
	v_bfe_u32 v24, v20, 16, 1
	v_add3_u32 v20, v20, v24, s71
	v_bfe_u32 v24, v21, 16, 1
	v_lshrrev_b32_e32 v20, 16, v20
	v_add3_u32 v21, v21, v24, s71
	v_and_or_b32 v24, v21, s70, v20
	v_bfe_u32 v20, v22, 16, 1
	v_add3_u32 v20, v22, v20, s71
	v_bfe_u32 v21, v23, 16, 1
	v_lshrrev_b32_e32 v20, 16, v20
	v_add3_u32 v21, v23, v21, s71
	v_and_or_b32 v25, v21, s70, v20
	v_add_co_u32_e32 v20, vcc, s1, v112
	v_pk_mul_f32 v[36:37], v[36:37], v[2:3] op_sel_hi:[1,0]
	s_nop 0
	v_addc_co_u32_e32 v21, vcc, 0, v113, vcc
	global_store_dwordx2 v[20:21], v[24:25], off
	global_load_dwordx4 v[196:199], v[96:97], off offset:1024
	global_load_dwordx4 v[200:203], v136, s[12:13]
	global_load_dwordx4 v[204:207], v136, s[10:11]
	global_load_dwordx4 v[208:211], v[96:97], off offset:2048
	global_load_dwordx4 v[212:215], v137, s[12:13]
	global_load_dwordx4 v[216:219], v137, s[10:11]
	global_load_dwordx4 v[220:223], v[96:97], off offset:3072
	global_load_dwordx4 v[224:227], v138, s[12:13]
	global_load_dwordx4 v[228:231], v138, s[10:11]
	global_load_dwordx4 v[232:235], v[98:99], off
	global_load_dwordx4 v[236:239], v129, s[12:13]
	global_load_dwordx4 v[240:243], v129, s[10:11]
	s_nop 0
	v_pk_mul_f32 v[34:35], v[38:39], v[2:3] op_sel_hi:[1,0]
	v_pk_mul_f32 v[18:19], v[18:19], v[2:3] op_sel_hi:[1,0]
	v_pk_mul_f32 v[16:17], v[16:17], v[2:3] op_sel_hi:[1,0]
	v_pk_mul_f32 v[14:15], v[14:15], v[2:3] op_sel_hi:[1,0]
	v_pk_mul_f32 v[12:13], v[12:13], v[2:3] op_sel_hi:[1,0]
	v_pk_mul_f32 v[10:11], v[10:11], v[2:3] op_sel_hi:[1,0]
	v_pk_mul_f32 v[8:9], v[8:9], v[2:3] op_sel_hi:[1,0]
	v_pk_mul_f32 v[6:7], v[6:7], v[2:3] op_sel_hi:[1,0]
	v_pk_mul_f32 v[4:5], v[4:5], v[2:3] op_sel_hi:[1,0]
	v_readlane_b32 s1, v255, 22
	s_cmp_ge_i32 s0, s1
	s_waitcnt vmcnt(11)
	v_pk_mul_f32 v[22:23], v[196:197], v[36:37]
	s_waitcnt vmcnt(10)
	v_pk_add_f32 v[26:27], v[200:201], 1.0 op_sel_hi:[1,0]
	v_pk_mul_f32 v[24:25], v[198:199], v[34:35]
	s_waitcnt vmcnt(9)
	v_pk_fma_f32 v[22:23], v[26:27], v[22:23], v[204:205]
	v_pk_add_f32 v[28:29], v[202:203], 1.0 op_sel_hi:[1,0]
	v_bfe_u32 v26, v22, 16, 1
	v_add3_u32 v22, v22, v26, s71
	v_bfe_u32 v26, v23, 16, 1
	v_pk_fma_f32 v[24:25], v[28:29], v[24:25], v[206:207]
	v_lshrrev_b32_e32 v22, 16, v22
	v_add3_u32 v23, v23, v26, s71
	v_and_or_b32 v22, v23, s70, v22
	v_bfe_u32 v23, v24, 16, 1
	v_add3_u32 v23, v24, v23, s71
	v_bfe_u32 v24, v25, 16, 1
	v_lshrrev_b32_e32 v23, 16, v23
	v_add3_u32 v24, v25, v24, s71
	v_and_or_b32 v23, v24, s70, v23
	global_store_dwordx2 v[20:21], v[22:23], off offset:512
	global_load_dwordx4 v[196:199], v[100:101], off
	global_load_dwordx4 v[200:203], v130, s[12:13]
	global_load_dwordx4 v[204:207], v130, s[10:11]
	s_nop 0
	v_pk_mul_f32 v[36:37], v[40:41], v[2:3] op_sel_hi:[1,0]
	v_pk_mul_f32 v[34:35], v[42:43], v[2:3] op_sel_hi:[1,0]
	s_waitcnt vmcnt(12)
	v_pk_mul_f32 v[22:23], v[208:209], v[36:37]
	s_waitcnt vmcnt(11)
	v_pk_add_f32 v[26:27], v[212:213], 1.0 op_sel_hi:[1,0]
	v_pk_mul_f32 v[24:25], v[210:211], v[34:35]
	s_waitcnt vmcnt(10)
	v_pk_fma_f32 v[22:23], v[26:27], v[22:23], v[216:217]
	v_pk_add_f32 v[28:29], v[214:215], 1.0 op_sel_hi:[1,0]
	v_bfe_u32 v26, v22, 16, 1
	v_add3_u32 v22, v22, v26, s71
	v_bfe_u32 v26, v23, 16, 1
	v_pk_fma_f32 v[24:25], v[28:29], v[24:25], v[218:219]
	v_lshrrev_b32_e32 v22, 16, v22
	v_add3_u32 v23, v23, v26, s71
	v_and_or_b32 v22, v23, s70, v22
	v_bfe_u32 v23, v24, 16, 1
	v_add3_u32 v23, v24, v23, s71
	v_bfe_u32 v24, v25, 16, 1
	v_lshrrev_b32_e32 v23, 16, v23
	v_add3_u32 v24, v25, v24, s71
	v_and_or_b32 v23, v24, s70, v23
	global_store_dwordx2 v[20:21], v[22:23], off offset:1024
	global_load_dwordx4 v[208:211], v[102:103], off
	global_load_dwordx4 v[212:215], v131, s[12:13]
	global_load_dwordx4 v[216:219], v131, s[10:11]
	s_nop 0
	v_pk_mul_f32 v[34:35], v[46:47], v[2:3] op_sel_hi:[1,0]
	v_pk_mul_f32 v[36:37], v[44:45], v[2:3] op_sel_hi:[1,0]
	s_waitcnt vmcnt(13)
; __device__ __forceinline__ unsigned pk2(float lo, float hi) { return f2bf(lo) | (f2bf(hi) << 16); }
; __device__ __forceinline__ void rowwise_phase(const Params& P, int mrows, bool first, int l_post, int j_post, int gate_idx, float coef, bool final_, int l_pre, int j_pre, int shift_idx, int scale_idx) {
;     ...
; #pragma unroll
;             for (int j = 0; j < 8; ++j) { const int c = 4 * lane + 256 * j; const f32x4 g4 = *(const f32x4*)(gp + c), sh = *(const f32x4*)(mb + shift_idx * DM + c), scl = *(const f32x4*)(mb + scale_idx * DM + c);
;                 const f32x4 h = (xv[j] * rs) * g4 * (scl + 1.f) + sh; u32x2 w; w.x = pk2(h.x, h.y); w.y = pk2(h.z, h.w); *(u32x2*)(hr + c) = w; }
	v_pk_mul_f32 v[24:25], v[34:35], v[222:223]
	v_pk_mul_f32 v[22:23], v[36:37], v[220:221]
	s_waitcnt vmcnt(12)
	v_pk_add_f32 v[28:29], v[226:227], 1.0 op_sel_hi:[1,0]
	v_pk_add_f32 v[26:27], v[224:225], 1.0 op_sel_hi:[1,0]
	s_waitcnt vmcnt(11)
	v_pk_fma_f32 v[24:25], v[24:25], v[28:29], v[230:231]
	v_pk_fma_f32 v[22:23], v[22:23], v[26:27], v[228:229]
	v_bfe_u32 v28, v24, 16, 1
	v_bfe_u32 v26, v22, 16, 1
	v_bfe_u32 v27, v23, 16, 1
	v_bfe_u32 v29, v25, 16, 1
	v_add3_u32 v22, v22, v26, s71
	v_add3_u32 v24, v24, v28, s71
	v_add3_u32 v23, v23, v27, s71
	v_add3_u32 v25, v25, v29, s71
	v_lshrrev_b32_e32 v22, 16, v22
	v_lshrrev_b32_e32 v24, 16, v24
	v_and_or_b32 v22, v23, s70, v22
	v_and_or_b32 v23, v25, s70, v24
	global_store_dwordx2 v[20:21], v[22:23], off offset:1536
	global_load_dwordx4 v[220:223], v[104:105], off
	global_load_dwordx4 v[224:227], v135, s[12:13]
	global_load_dwordx4 v[228:231], v135, s[10:11]
	s_nop 0
	s_waitcnt vmcnt(14)
	v_pk_mul_f32 v[16:17], v[16:17], v[232:233]
	v_pk_mul_f32 v[18:19], v[18:19], v[234:235]
	s_waitcnt vmcnt(13)
	v_pk_add_f32 v[22:23], v[238:239], 1.0 op_sel_hi:[1,0]
	v_pk_add_f32 v[24:25], v[236:237], 1.0 op_sel_hi:[1,0]
	s_waitcnt vmcnt(12)
	v_pk_fma_f32 v[18:19], v[18:19], v[22:23], v[242:243]
	v_pk_fma_f32 v[16:17], v[16:17], v[24:25], v[240:241]
	v_bfe_u32 v24, v18, 16, 1
	v_bfe_u32 v22, v16, 16, 1
	v_bfe_u32 v23, v17, 16, 1
	v_bfe_u32 v25, v19, 16, 1
	v_add3_u32 v16, v16, v22, s71
	v_add3_u32 v18, v18, v24, s71
	v_add3_u32 v17, v17, v23, s71
	v_add3_u32 v19, v19, v25, s71
	v_lshrrev_b32_e32 v16, 16, v16
	v_lshrrev_b32_e32 v18, 16, v18
	v_and_or_b32 v16, v17, s70, v16
	v_and_or_b32 v17, v19, s70, v18
	global_store_dwordx2 v[20:21], v[16:17], off offset:2048
	s_nop 0
	s_waitcnt vmcnt(11)
	v_pk_mul_f32 v[12:13], v[12:13], v[196:197]
	v_pk_mul_f32 v[14:15], v[14:15], v[198:199]
	s_waitcnt vmcnt(10)
	v_pk_add_f32 v[16:17], v[202:203], 1.0 op_sel_hi:[1,0]
	v_pk_add_f32 v[18:19], v[200:201], 1.0 op_sel_hi:[1,0]
	s_waitcnt vmcnt(9)
	v_pk_fma_f32 v[14:15], v[14:15], v[16:17], v[206:207]
	v_pk_fma_f32 v[12:13], v[12:13], v[18:19], v[204:205]
	v_bfe_u32 v18, v14, 16, 1
	v_bfe_u32 v16, v12, 16, 1
	v_bfe_u32 v17, v13, 16, 1
	v_bfe_u32 v19, v15, 16, 1
	v_add3_u32 v12, v12, v16, s71
	v_add3_u32 v14, v14, v18, s71
	v_add3_u32 v13, v13, v17, s71
	v_add3_u32 v15, v15, v19, s71
	v_lshrrev_b32_e32 v12, 16, v12
	v_lshrrev_b32_e32 v14, 16, v14
	v_and_or_b32 v12, v13, s70, v12
	v_and_or_b32 v13, v15, s70, v14
	global_store_dwordx2 v[20:21], v[12:13], off offset:2560
	s_nop 0
	s_waitcnt vmcnt(8)
	v_pk_mul_f32 v[8:9], v[8:9], v[208:209]
	v_pk_mul_f32 v[10:11], v[10:11], v[210:211]
	s_waitcnt vmcnt(7)
	v_pk_add_f32 v[12:13], v[214:215], 1.0 op_sel_hi:[1,0]
	v_pk_add_f32 v[14:15], v[212:213], 1.0 op_sel_hi:[1,0]
	s_waitcnt vmcnt(6)
	v_pk_fma_f32 v[10:11], v[10:11], v[12:13], v[218:219]
	v_pk_fma_f32 v[8:9], v[8:9], v[14:15], v[216:217]
	v_bfe_u32 v14, v10, 16, 1
	v_bfe_u32 v12, v8, 16, 1
	v_bfe_u32 v13, v9, 16, 1
	v_bfe_u32 v15, v11, 16, 1
	v_add3_u32 v8, v8, v12, s71
	v_add3_u32 v10, v10, v14, s71
	v_add3_u32 v9, v9, v13, s71
	v_add3_u32 v11, v11, v15, s71
	v_lshrrev_b32_e32 v8, 16, v8
	v_lshrrev_b32_e32 v10, 16, v10
	v_and_or_b32 v8, v9, s70, v8
	v_and_or_b32 v9, v11, s70, v10
	global_store_dwordx2 v[20:21], v[8:9], off offset:3072
	s_nop 0
	s_waitcnt vmcnt(5)
	v_pk_mul_f32 v[4:5], v[4:5], v[220:221]
	v_pk_mul_f32 v[6:7], v[6:7], v[222:223]
	s_waitcnt vmcnt(4)
	v_pk_add_f32 v[8:9], v[226:227], 1.0 op_sel_hi:[1,0]
	v_pk_add_f32 v[10:11], v[224:225], 1.0 op_sel_hi:[1,0]
	s_waitcnt vmcnt(3)
	v_pk_fma_f32 v[6:7], v[6:7], v[8:9], v[230:231]
	v_pk_fma_f32 v[4:5], v[4:5], v[10:11], v[228:229]
	v_bfe_u32 v9, v6, 16, 1
	v_bfe_u32 v2, v4, 16, 1
	v_bfe_u32 v8, v5, 16, 1
	v_bfe_u32 v10, v7, 16, 1
	v_add3_u32 v2, v4, v2, s71
	v_add3_u32 v4, v5, v8, s71
	v_add3_u32 v5, v6, v9, s71
	v_add3_u32 v6, v7, v10, s71
	v_lshrrev_b32_e32 v2, 16, v2
	v_lshrrev_b32_e32 v5, 16, v5
	v_and_or_b32 v4, v4, s70, v2
	v_and_or_b32 v5, v6, s70, v5
	global_store_dwordx2 v[20:21], v[4:5], off offset:3584
	s_cbranch_scc1 .LBB0_43

; __device__ __forceinline__ float dot4(f32x4 a) { return (a.x * a.x + a.y * a.y) + (a.z * a.z + a.w * a.w); }
; __device__ __forceinline__ void rowwise_phase(const Params& P, int mrows, bool first, int l_post, int j_post, int gate_idx, float coef, bool final_, int l_pre, int j_pre, int shift_idx, int scale_idx) {
;     ...
;             const float* gp = P.norm_post + (size_t)(l_post * 3 + j_post) * DM; const float* mg = MOD + (size_t)(l_post * 5 + b) * NMODV + gate_idx * DM;
;             float sxx = 0.f, sxt = 0.f, stt = 0.f;
; #pragma unroll
;             for (int j = 0; j < 8; ++j) { const int c = 4 * lane + 256 * j; xv[j] = *(const f32x4*)(xr + c); const f32x4 g4 = *(const f32x4*)(gp + c), m4 = *(const f32x4*)(mg + c);
;                 ss += dot4(yv[j]); yv[j] = yv[j] * g4 * m4; sxx += dot4(xv[j]); stt += dot4(yv[j]);
;                 const f32x4 xt = xv[j] * yv[j]; sxt += (xt.x + xt.y) + (xt.z + xt.w); }
.LBB0_284:
	s_lshl_b64 s[18:19], s[18:19], 13
	s_add_u32 s18, s20, s18
	s_addc_u32 s19, s21, s19
	s_min_i32 s20, s6, 0x2000
	v_readlane_b32 s24, v255, 14
	s_ashr_i32 s20, s20, 11
	v_readlane_b32 s25, v255, 15
	s_mul_i32 s21, s24, 5
	global_load_dwordx4 v[82:85], v[56:57], off
	global_load_dwordx4 v[86:89], v[56:57], off offset:1024
	global_load_dwordx4 v[90:93], v[56:57], off offset:2048
	s_add_i32 s25, s20, s21
	global_load_dwordx4 v[44:47], v106, s[18:19]
	global_load_dwordx4 v[40:43], v106, s[18:19] offset:1024
	global_load_dwordx4 v[36:39], v106, s[18:19] offset:2048
	s_mul_hi_i32 s24, s25, 0x12000
	s_mul_i32 s25, s25, 0x12000
	s_add_u32 s20, s28, s25
	s_addc_u32 s21, s29, s24
	global_load_dwordx4 v[94:97], v106, s[20:21]
	global_load_dwordx4 v[114:117], v106, s[20:21] offset:1024
	global_load_dwordx4 v[118:121], v106, s[20:21] offset:2048
	s_waitcnt vmcnt(9)
	v_pk_mul_f32 v[48:49], v[30:31], v[30:31]
	v_pk_mul_f32 v[50:51], v[28:29], v[28:29]
	global_load_dwordx4 v[122:125], v[56:57], off offset:3072
	global_load_dwordx4 v[126:129], v[58:59], off
	v_pk_mov_b32 v[52:53], v[50:51], v[48:49] op_sel:[1,0]
	v_mov_b32_e32 v51, v49
	v_pk_add_f32 v[48:49], v[52:53], v[50:51]
	v_mov_b32_e32 v99, v4
	v_pk_add_f32 v[144:145], v[48:49], v[48:49] op_sel_hi:[0,1]
	global_load_dwordx4 v[48:51], v106, s[18:19] offset:3072
	global_load_dwordx4 v[136:139], v106, s[20:21] offset:3072
	global_load_dwordx4 v[52:55], v107, s[18:19]
	global_load_dwordx4 v[140:143], v107, s[20:21]
	v_mov_b32_e32 v131, v6
	v_mov_b32_e32 v98, v20
	v_mov_b32_e32 v130, v22
	v_mul_f32_e32 v144, v10, v10
	s_mov_b32 s3, 0x800000
	v_lshl_add_u64 v[80:81], v[80:81], 0, s[16:17]
	s_waitcnt vmcnt(14)
	v_pk_mul_f32 v[84:85], v[6:7], v[84:85]
	v_pk_mul_f32 v[82:83], v[4:5], v[82:83]
	v_mov_b32_e32 v4, v21
	v_mov_b32_e32 v6, v23
	v_pk_mul_f32 v[4:5], v[4:5], v[4:5]
	v_pk_mul_f32 v[6:7], v[6:7], v[6:7]
	v_pk_fma_f32 v[4:5], v[98:99], v[98:99], v[4:5]
	v_pk_fma_f32 v[6:7], v[130:131], v[130:131], v[6:7]
	s_waitcnt vmcnt(13)
	v_pk_mul_f32 v[88:89], v[22:23], v[88:89]
	v_pk_mul_f32 v[86:87], v[20:21], v[86:87]
	s_waitcnt vmcnt(12)
	v_pk_mul_f32 v[30:31], v[30:31], v[92:93]
	v_pk_add_f32 v[4:5], v[4:5], v[6:7]
	s_waitcnt vmcnt(11)
	v_mov_b32_e32 v20, v45
	s_waitcnt vmcnt(10)
	v_mov_b32_e32 v21, v41
	v_mov_b32_e32 v22, v46
	v_mov_b32_e32 v23, v42
	s_waitcnt vmcnt(9)
	v_pk_mul_f32 v[92:93], v[38:39], v[38:39]
	v_pk_mul_f32 v[98:99], v[36:37], v[36:37]
	v_pk_mul_f32 v[28:29], v[28:29], v[90:91]
	v_mov_b32_e32 v6, v44
	v_mov_b32_e32 v7, v40
	v_mov_b32_e32 v90, v47
	v_mov_b32_e32 v91, v43
	v_pk_add_f32 v[130:131], v[4:5], v[4:5] op_sel_hi:[0,1]
	v_pk_mul_f32 v[4:5], v[20:21], v[20:21]
	v_pk_mul_f32 v[20:21], v[22:23], v[22:23]
	v_pk_mov_b32 v[22:23], v[98:99], v[92:93] op_sel:[1,0]
	v_mov_b32_e32 v99, v93
	v_pk_fma_f32 v[4:5], v[6:7], v[6:7], v[4:5]
	v_pk_fma_f32 v[6:7], v[90:91], v[90:91], v[20:21]
	v_pk_add_f32 v[146:147], v[98:99], v[22:23]
	s_waitcnt vmcnt(8)
	v_pk_mul_f32 v[20:21], v[96:97], v[84:85]
	v_pk_mul_f32 v[22:23], v[94:95], v[82:83]
	s_waitcnt vmcnt(7)
	v_pk_mul_f32 v[82:83], v[116:117], v[88:89]
	v_pk_mul_f32 v[84:85], v[114:115], v[86:87]
	s_waitcnt vmcnt(6)
	v_pk_mul_f32 v[86:87], v[120:121], v[30:31]
	v_pk_mul_f32 v[88:89], v[118:119], v[28:29]
	v_mul_f32_e32 v2, v21, v21
	v_pk_mul_f32 v[28:29], v[46:47], v[20:21]
	v_pk_mul_f32 v[30:31], v[44:45], v[22:23]
	v_pk_mul_f32 v[98:99], v[42:43], v[82:83]
	v_pk_mul_f32 v[114:115], v[40:41], v[84:85]
	v_pk_add_f32 v[148:149], v[4:5], v[6:7]
	v_mul_f32_e32 v4, v22, v22
	v_mul_f32_e32 v6, v23, v23
	v_mul_f32_e32 v90, v84, v84
	v_mul_f32_e32 v92, v85, v85
	v_mul_f32_e32 v94, v82, v82
	v_mul_f32_e32 v96, v83, v83
	v_pk_fma_f32 v[152:153], v[20:21], v[20:21], v[2:3] op_sel_hi:[1,1,0]
	v_add_f32_e32 v5, v30, v31
	v_add_f32_e32 v7, v28, v29
	v_pk_mul_f32 v[28:29], v[38:39], v[86:87]
	v_pk_mul_f32 v[30:31], v[36:37], v[88:89]
	v_mov_b32_e32 v91, v114
	v_mov_b32_e32 v93, v115
	v_mov_b32_e32 v95, v98
	v_mov_b32_e32 v97, v99
	v_mul_f32_e32 v116, v88, v88
	v_mul_f32_e32 v118, v89, v89
	v_mul_f32_e32 v120, v86, v86
	v_mul_f32_e32 v150, v87, v87
	v_pk_add_f32 v[4:5], v[4:5], v[6:7]
	v_mov_b32_e32 v153, v3
	v_pk_add_f32 v[6:7], v[90:91], v[92:93]
	v_pk_add_f32 v[90:91], v[94:95], v[96:97]
	v_mov_b32_e32 v117, v30
	v_mov_b32_e32 v119, v31
	v_mov_b32_e32 v121, v28
	v_mov_b32_e32 v151, v29
	v_pk_add_f32 v[4:5], v[4:5], v[152:153]
	v_pk_add_f32 v[6:7], v[6:7], v[90:91]
	v_pk_add_f32 v[30:31], v[116:117], v[118:119]
	v_pk_add_f32 v[28:29], v[120:121], v[150:151]
	v_pk_add_f32 v[90:91], v[4:5], v[6:7]
	v_pk_add_f32 v[28:29], v[30:31], v[28:29]
	v_mul_f32_e32 v2, v12, v12
	v_pk_add_f32 v[98:99], v[90:91], v[28:29]
	v_pk_fma_f32 v[28:29], v[12:13], v[12:13], v[2:3] op_sel_hi:[1,1,0]
	v_mul_f32_e32 v2, v14, v14
	v_pk_fma_f32 v[30:31], v[14:15], v[14:15], v[2:3] op_sel_hi:[1,1,0]
	s_waitcnt vmcnt(5)
	v_pk_mul_f32 v[14:15], v[14:15], v[124:125]
	v_pk_mul_f32 v[12:13], v[12:13], v[122:123]
	global_load_dwordx4 v[94:97], v[60:61], off
	global_load_dwordx4 v[4:7], v108, s[18:19]
	global_load_dwordx4 v[114:117], v108, s[20:21]
	s_waitcnt vmcnt(5)
; __device__ __forceinline__ float dot4(f32x4 a) { return (a.x * a.x + a.y * a.y) + (a.z * a.z + a.w * a.w); }
; __device__ __forceinline__ void rowwise_phase(const Params& P, int mrows, bool first, int l_post, int j_post, int gate_idx, float coef, bool final_, int l_pre, int j_pre, int shift_idx, int scale_idx) {
;     ...
;             for (int j = 0; j < 8; ++j) { const int c = 4 * lane + 256 * j; xv[j] = *(const f32x4*)(xr + c); const f32x4 g4 = *(const f32x4*)(gp + c), m4 = *(const f32x4*)(mg + c);
;                 ss += dot4(yv[j]); yv[j] = yv[j] * g4 * m4; sxx += dot4(xv[j]); stt += dot4(yv[j]);
;                 const f32x4 xt = xv[j] * yv[j]; sxt += (xt.x + xt.y) + (xt.z + xt.w); }
; #pragma unroll
;             for (int o = 1; o < 64; o <<= 1) { ss += __shfl_xor(ss, o); sxx += __shfl_xor(sxx, o); sxt += __shfl_xor(sxt, o); stt += __shfl_xor(stt, o); }
;             const float rs = rsqrtf(ss * (1.f / DM) + EPS) * coef;
	v_pk_mul_f32 v[90:91], v[138:139], v[14:15]
	v_pk_mul_f32 v[92:93], v[136:137], v[12:13]
	global_load_dwordx4 v[118:121], v[62:63], off
	global_load_dwordx4 v[12:15], v109, s[18:19]
	global_load_dwordx4 v[122:125], v109, s[20:21]
	v_pk_mul_f32 v[154:155], v[50:51], v[90:91]
	v_pk_mul_f32 v[156:157], v[48:49], v[92:93]
	v_mul_f32_e32 v136, v92, v92
	v_mul_f32_e32 v138, v93, v93
	v_mul_f32_e32 v150, v90, v90
	v_mul_f32_e32 v152, v91, v91
	v_mov_b32_e32 v137, v156
	v_mov_b32_e32 v139, v157
	v_mov_b32_e32 v151, v154
	v_mov_b32_e32 v153, v155
	v_mul_f32_e32 v28, v8, v8
	v_mul_f32_e32 v30, v9, v9
	v_mul_f32_e32 v130, v11, v11
	v_pk_add_f32 v[136:137], v[136:137], v[138:139]
	v_pk_add_f32 v[138:139], v[150:151], v[152:153]
	v_pk_add_f32 v[28:29], v[28:29], v[30:31]
	v_pk_add_f32 v[30:31], v[144:145], v[130:131]
	v_pk_add_f32 v[150:151], v[136:137], v[138:139]
	v_pk_add_f32 v[28:29], v[28:29], v[30:31]
	global_load_dwordx4 v[136:139], v[64:65], off
	v_pk_add_f32 v[130:131], v[28:29], v[28:29] op_sel_hi:[0,1]
	v_pk_mul_f32 v[10:11], v[10:11], v[128:129]
	v_pk_mul_f32 v[144:145], v[8:9], v[126:127]
	global_load_dwordx4 v[28:31], v110, s[18:19]
	global_load_dwordx4 v[126:129], v110, s[20:21]
	s_waitcnt vmcnt(9)
	v_pk_mul_f32 v[8:9], v[142:143], v[10:11]
	v_pk_mul_f32 v[10:11], v[140:141], v[144:145]
	v_mul_f32_e32 v2, v52, v52
	v_mul_f32_e32 v130, v53, v53
	v_pk_add_f32 v[140:141], v[148:149], v[148:149] op_sel:[0,1] op_sel_hi:[1,0]
	v_pk_add_f32 v[142:143], v[146:147], v[146:147] op_sel:[0,1] op_sel_hi:[1,0]
	v_mov_b32_e32 v141, v2
	v_mov_b32_e32 v143, v130
	v_mul_f32_e32 v2, v49, v49
	v_pk_add_f32 v[140:141], v[140:141], v[142:143]
	v_pk_fma_f32 v[142:143], v[48:49], v[48:49], v[2:3] op_sel_hi:[1,1,0]
	v_mul_f32_e32 v2, v51, v51
	v_mul_f32_e32 v132, v54, v54
	v_mul_f32_e32 v135, v55, v55
	v_pk_fma_f32 v[144:145], v[50:51], v[50:51], v[2:3] op_sel_hi:[1,1,0]
	v_mov_b32_e32 v143, v135
	v_mov_b32_e32 v145, v132
	v_pk_add_f32 v[142:143], v[142:143], v[144:145]
	v_pk_mul_f32 v[152:153], v[54:55], v[8:9]
	v_pk_mul_f32 v[154:155], v[52:53], v[10:11]
	v_pk_add_f32 v[140:141], v[140:141], v[142:143]
	v_mul_f32_e32 v142, v10, v10
	v_mul_f32_e32 v144, v11, v11
	v_mul_f32_e32 v146, v8, v8
	v_mul_f32_e32 v148, v9, v9
	v_mov_b32_e32 v143, v154
	v_mov_b32_e32 v145, v155
	v_mov_b32_e32 v147, v152
	v_mov_b32_e32 v149, v153
	v_pk_add_f32 v[142:143], v[142:143], v[144:145]
	v_pk_add_f32 v[144:145], v[146:147], v[148:149]
	v_pk_mul_f32 v[146:147], v[18:19], v[18:19]
	v_pk_mul_f32 v[148:149], v[16:17], v[16:17]
	v_mul_f32_e32 v2, v24, v24
	v_pk_mov_b32 v[152:153], v[148:149], v[146:147] op_sel:[1,0]
	v_mov_b32_e32 v149, v147
	v_pk_add_f32 v[146:147], v[152:153], v[148:149]
	v_pk_fma_f32 v[160:161], v[24:25], v[24:25], v[2:3] op_sel_hi:[1,1,0]
	v_mul_f32_e32 v2, v26, v26
	v_pk_add_f32 v[146:147], v[146:147], v[146:147] op_sel_hi:[0,1]
	v_pk_fma_f32 v[162:163], v[26:27], v[26:27], v[2:3] op_sel_hi:[1,1,0]
	v_mul_f32_e32 v160, v32, v32
	v_mul_f32_e32 v162, v33, v33
	v_mul_f32_e32 v146, v34, v34
	v_mul_f32_e32 v130, v35, v35
	s_lshl_b64 s[18:19], s[22:23], 13
	s_add_u32 s20, s26, s25
	s_addc_u32 s21, s27, s24
	s_waitcnt vmcnt(8)
	v_pk_mul_f32 v[18:19], v[18:19], v[96:97]
	v_pk_mul_f32 v[16:17], v[16:17], v[94:95]
	s_waitcnt vmcnt(7)
	v_pk_mul_f32 v[94:95], v[6:7], v[6:7]
	s_waitcnt vmcnt(5)
	v_pk_mul_f32 v[26:27], v[26:27], v[120:121]
	v_pk_mul_f32 v[24:25], v[24:25], v[118:119]
	s_waitcnt vmcnt(3)
	v_pk_mul_f32 v[118:119], v[124:125], v[26:27]
	v_pk_mul_f32 v[120:121], v[122:123], v[24:25]
	v_pk_add_f32 v[122:123], v[160:161], v[162:163]
	v_pk_add_f32 v[124:125], v[146:147], v[130:131]
	v_pk_mul_f32 v[96:97], v[4:5], v[4:5]
	v_pk_add_f32 v[122:123], v[122:123], v[124:125]
	v_pk_mul_f32 v[16:17], v[114:115], v[16:17]
	v_add_f32_e32 v2, v122, v123
	ds_bpermute_b32 v25, v100, v2
	v_pk_mov_b32 v[114:115], v[96:97], v[94:95] op_sel:[1,0]
	v_mov_b32_e32 v97, v95
	v_pk_add_f32 v[114:115], v[96:97], v[114:115]
	v_pk_mul_f32 v[124:125], v[12:13], v[120:121]
	s_waitcnt lgkmcnt(0)
	v_add_f32_e32 v2, v2, v25
	ds_bpermute_b32 v25, v101, v2
	v_pk_mul_f32 v[18:19], v[116:117], v[18:19]
	v_mul_f32_e32 v116, v16, v16
	v_mul_f32_e32 v148, v17, v17
	v_mul_f32_e32 v152, v18, v18
	s_waitcnt lgkmcnt(0)
	v_add_f32_e32 v2, v2, v25
	ds_bpermute_b32 v25, v102, v2
	s_waitcnt vmcnt(2)
	v_pk_mul_f32 v[32:33], v[32:33], v[136:137]
	v_pk_mul_f32 v[34:35], v[34:35], v[138:139]
	s_waitcnt vmcnt(1)
	v_mul_f32_e32 v27, v28, v28
	s_waitcnt vmcnt(0)
	v_pk_mul_f32 v[126:127], v[126:127], v[32:33]
	v_pk_add_f32 v[32:33], v[140:141], v[140:141] op_sel:[0,1] op_sel_hi:[1,0]
	s_waitcnt lgkmcnt(0)
	v_add_f32_e32 v25, v2, v25
	v_mov_b32_e32 v33, v27
	ds_bpermute_b32 v27, v103, v25
	v_mul_f32_e32 v2, v13, v13
	v_pk_fma_f32 v[130:131], v[12:13], v[12:13], v[2:3] op_sel_hi:[1,1,0]
	v_mul_f32_e32 v2, v15, v15
	v_pk_fma_f32 v[136:137], v[14:15], v[14:15], v[2:3] op_sel_hi:[1,1,0]
	s_waitcnt lgkmcnt(0)
	v_add_f32_e32 v25, v25, v27
	ds_bpermute_b32 v27, v104, v25
	v_pk_mul_f32 v[128:129], v[128:129], v[34:35]
	v_mul_f32_e32 v95, v29, v29
	v_pk_add_f32 v[34:35], v[114:115], v[114:115] op_sel:[0,1] op_sel_hi:[1,0]
	v_mul_f32_e32 v154, v19, v19
	s_waitcnt lgkmcnt(0)
	v_add_f32_e32 v2, v25, v27
	ds_bpermute_b32 v25, v105, v2
	v_mov_b32_e32 v35, v95
	v_pk_add_f32 v[114:115], v[32:33], v[34:35]
	v_pk_add_f32 v[32:33], v[98:99], v[150:151]
	v_pk_add_f32 v[34:35], v[142:143], v[144:145]
	s_waitcnt lgkmcnt(0)
; __device__ __forceinline__ unsigned pk2(float lo, float hi) { return f2bf(lo) | (f2bf(hi) << 16); }
; __device__ __forceinline__ float dot4(f32x4 a) { return (a.x * a.x + a.y * a.y) + (a.z * a.z + a.w * a.w); }
; __device__ __forceinline__ void rowwise_phase(const Params& P, int mrows, bool first, int l_post, int j_post, int gate_idx, float coef, bool final_, int l_pre, int j_pre, int shift_idx, int scale_idx) {
;     ...
;             const float rs = rsqrtf(ss * (1.f / DM) + EPS) * coef;
;             ss_new = sxx + 2.f * rs * sxt + rs * rs * stt;
; #pragma unroll
;             for (int j = 0; j < 8; ++j) xv[j] += yv[j] * rs;
;         }
;         if (final_) {
;             float* o = P.out + (size_t)row * DM;
; #pragma unroll
;             for (int j = 0; j < 8; ++j) *(f32x4*)(o + 4 * lane + 256 * j) = xv[j];
;             continue;
;         }
;         {
;             float* xr = X + (size_t)row * DM; float ss = 0.f;
; #pragma unroll
;             for (int j = 0; j < 8; ++j) { if (!first) *(f32x4*)(xr + 4 * lane + 256 * j) = xv[j]; else ss += dot4(xv[j]); }
;             if (first) ss = wave_sum(ss); else ss = ss_new;
;             const float rs = rsqrtf(ss * (1.f / DM) + EPS);
;             const float* gp = P.norm_pre + (size_t)(l_pre * 3 + j_pre) * DM; const float* mb = MOD + (size_t)(l_pre * 5 + b) * NMODV;
;             bf16* hr = H + (size_t)row * DM;
; #pragma unroll
;             for (int j = 0; j < 8; ++j) { const int c = 4 * lane + 256 * j; const f32x4 g4 = *(const f32x4*)(gp + c), sh = *(const f32x4*)(mb + shift_idx * DM + c), scl = *(const f32x4*)(mb + scale_idx * DM + c);
;                 const f32x4 h = (xv[j] * rs) * g4 * (scl + 1.f) + sh; u32x2 w; w.x = pk2(h.x, h.y); w.y = pk2(h.z, h.w); *(u32x2*)(hr + c) = w; }
	v_add_f32_e32 v2, v2, v25
	v_fmamk_f32 v2, v2, 0x3a000000, v169
	v_mul_f32_e32 v25, 0x4b800000, v2
	v_cmp_gt_f32_e32 vcc, s3, v2
	v_pk_add_f32 v[98:99], v[32:33], v[34:35]
	v_pk_mul_f32 v[156:157], v[6:7], v[18:19]
	v_cndmask_b32_e32 v2, v2, v25, vcc
	v_rsq_f32_e32 v2, v2
	v_pk_mul_f32 v[158:159], v[4:5], v[16:17]
	v_pk_mul_f32 v[122:123], v[14:15], v[118:119]
	v_mul_f32_e32 v97, v30, v30
	v_mul_f32_e32 v25, 0x45800000, v2
	v_cndmask_b32_e32 v2, v2, v25, vcc
	v_mul_f32_e32 v132, 0.5, v2
	v_pk_fma_f32 v[34:35], v[20:21], v[132:133], v[46:47] op_sel_hi:[1,0,1]
	v_pk_fma_f32 v[32:33], v[22:23], v[132:133], v[44:45] op_sel_hi:[1,0,1]
	v_pk_fma_f32 v[22:23], v[8:9], v[132:133], v[54:55] op_sel_hi:[1,0,1]
	v_pk_fma_f32 v[8:9], v[120:121], v[132:133], v[12:13] op_sel_hi:[1,0,1]
	v_lshl_add_u64 v[12:13], v[0:1], 0, s[18:19]
	s_movk_i32 s18, 0x1000
	v_pk_fma_f32 v[42:43], v[82:83], v[132:133], v[42:43] op_sel_hi:[1,0,1]
	v_pk_fma_f32 v[40:41], v[84:85], v[132:133], v[40:41] op_sel_hi:[1,0,1]
	v_pk_fma_f32 v[38:39], v[86:87], v[132:133], v[38:39] op_sel_hi:[1,0,1]
	v_pk_fma_f32 v[36:37], v[88:89], v[132:133], v[36:37] op_sel_hi:[1,0,1]
	v_pk_fma_f32 v[46:47], v[90:91], v[132:133], v[50:51] op_sel_hi:[1,0,1]
	v_pk_fma_f32 v[44:45], v[92:93], v[132:133], v[48:49] op_sel_hi:[1,0,1]
	global_store_dwordx4 v[12:13], v[32:35], off
	global_store_dwordx4 v[12:13], v[40:43], off offset:1024
	global_store_dwordx4 v[12:13], v[36:39], off offset:2048
	global_store_dwordx4 v[12:13], v[44:47], off offset:3072
	v_add_co_u32_e32 v12, vcc, s18, v12
	s_add_u32 s18, s20, 0x6000
	v_pk_fma_f32 v[20:21], v[10:11], v[132:133], v[52:53] op_sel_hi:[1,0,1]
	v_addc_co_u32_e32 v13, vcc, 0, v13, vcc
	s_addc_u32 s19, s21, 0
	v_pk_fma_f32 v[18:19], v[18:19], v[132:133], v[6:7] op_sel_hi:[1,0,1]
	v_pk_fma_f32 v[16:17], v[16:17], v[132:133], v[4:5] op_sel_hi:[1,0,1]
	v_pk_fma_f32 v[10:11], v[118:119], v[132:133], v[14:15] op_sel_hi:[1,0,1]
	v_pk_fma_f32 v[6:7], v[128:129], v[132:133], v[30:31] op_sel_hi:[1,0,1]
	v_pk_fma_f32 v[4:5], v[126:127], v[132:133], v[28:29] op_sel_hi:[1,0,1]
	global_store_dwordx4 v[12:13], v[20:23], off
	global_store_dwordx4 v[12:13], v[16:19], off offset:1024
	global_store_dwordx4 v[12:13], v[8:11], off offset:2048
	global_store_dwordx4 v[12:13], v[4:7], off offset:3072
	s_add_u32 s20, s20, 0x8000
	v_mul_f32_e32 v117, v31, v31
	v_pk_mul_f32 v[162:163], v[30:31], v[128:129]
	v_pk_mul_f32 v[164:165], v[28:29], v[126:127]
	s_addc_u32 s21, s21, 0
	global_load_dwordx4 v[12:15], v[66:67], off
	global_load_dwordx4 v[28:31], v106, s[18:19]
	global_load_dwordx4 v[48:51], v106, s[20:21]
	v_mov_b32_e32 v131, v117
	v_mov_b32_e32 v117, v158
	v_mov_b32_e32 v149, v159
	v_mov_b32_e32 v153, v156
	v_mov_b32_e32 v155, v157
	v_mul_f32_e32 v94, v120, v120
	v_mul_f32_e32 v96, v121, v121
	v_mul_f32_e32 v24, v118, v118
	v_mul_f32_e32 v26, v119, v119
	v_mov_b32_e32 v137, v97
	v_pk_add_f32 v[116:117], v[116:117], v[148:149]
	v_pk_add_f32 v[142:143], v[152:153], v[154:155]
	v_mov_b32_e32 v95, v124
	v_mov_b32_e32 v97, v125
	v_mov_b32_e32 v25, v122
	v_mov_b32_e32 v27, v123
	v_pk_add_f32 v[52:53], v[116:117], v[142:143]
	v_pk_add_f32 v[54:55], v[94:95], v[96:97]
	v_pk_add_f32 v[24:25], v[24:25], v[26:27]
	v_mul_f32_e32 v138, v126, v126
	v_mul_f32_e32 v140, v127, v127
	v_mul_f32_e32 v146, v128, v128
	v_mul_f32_e32 v160, v129, v129
	v_pk_add_f32 v[52:53], v[98:99], v[52:53]
	v_pk_add_f32 v[24:25], v[54:55], v[24:25]
	v_mov_b32_e32 v139, v164
	v_mov_b32_e32 v141, v165
	v_mov_b32_e32 v147, v162
	v_mov_b32_e32 v161, v163
	v_pk_add_f32 v[24:25], v[52:53], v[24:25]
	v_pk_add_f32 v[26:27], v[138:139], v[140:141]
	v_pk_add_f32 v[52:53], v[146:147], v[160:161]
	s_lshl_b64 s[22:23], s[22:23], 12
	v_pk_add_f32 v[26:27], v[26:27], v[52:53]
	v_pk_add_f32 v[52:53], v[130:131], v[136:137]
	v_pk_add_f32 v[24:25], v[24:25], v[26:27]
	v_pk_add_f32 v[52:53], v[114:115], v[52:53]
	ds_bpermute_b32 v27, v100, v25
	ds_bpermute_b32 v26, v100, v24
	v_add_f32_e32 v2, v52, v53
	ds_bpermute_b32 v52, v100, v2
	s_add_u32 s6, s6, s8
	s_addc_u32 s7, s7, s9
	s_waitcnt lgkmcnt(1)
	v_pk_add_f32 v[24:25], v[24:25], v[26:27]
	ds_bpermute_b32 v27, v101, v25
	ds_bpermute_b32 v26, v101, v24
	s_waitcnt lgkmcnt(2)
	v_add_f32_e32 v2, v2, v52
	ds_bpermute_b32 v52, v101, v2
	s_cmpk_gt_i32 s6, 0x23ff
	s_waitcnt lgkmcnt(1)
	v_pk_add_f32 v[24:25], v[24:25], v[26:27]
	ds_bpermute_b32 v27, v102, v25
	ds_bpermute_b32 v26, v102, v24
	s_waitcnt lgkmcnt(2)
	v_add_f32_e32 v2, v2, v52
	ds_bpermute_b32 v52, v102, v2
	s_waitcnt lgkmcnt(1)
	v_pk_add_f32 v[24:25], v[24:25], v[26:27]
	ds_bpermute_b32 v27, v103, v25
	ds_bpermute_b32 v26, v103, v24
	s_waitcnt lgkmcnt(2)
	v_add_f32_e32 v2, v2, v52
	ds_bpermute_b32 v52, v103, v2
	s_waitcnt lgkmcnt(1)
	v_pk_add_f32 v[24:25], v[24:25], v[26:27]
	ds_bpermute_b32 v27, v104, v25
	ds_bpermute_b32 v26, v104, v24
	s_waitcnt lgkmcnt(2)
	v_add_f32_e32 v2, v2, v52
	ds_bpermute_b32 v52, v104, v2
	s_waitcnt lgkmcnt(1)
	v_pk_add_f32 v[24:25], v[24:25], v[26:27]
	ds_bpermute_b32 v27, v105, v25
	ds_bpermute_b32 v26, v105, v24
	s_waitcnt lgkmcnt(2)
	v_add_f32_e32 v2, v2, v52
	ds_bpermute_b32 v52, v105, v2
	s_waitcnt lgkmcnt(1)
	v_pk_add_f32 v[24:25], v[24:25], v[26:27]
	v_pk_mul_f32 v[26:27], v[132:133], v[132:133] op_sel_hi:[0,1]
	v_pk_mul_f32 v[24:25], v[24:25], v[26:27]
	s_waitcnt lgkmcnt(0)
	v_add_f32_e32 v2, v2, v52
	v_add_f32_e32 v2, v2, v25
	v_add_f32_e32 v2, v24, v2
	v_fmamk_f32 v2, v2, 0x3a000000, v169
	v_mul_f32_e32 v24, 0x4b800000, v2
	v_cmp_gt_f32_e32 vcc, s3, v2
	s_nop 1
	v_cndmask_b32_e32 v2, v2, v24, vcc
	v_rsq_f32_e32 v2, v2
	s_nop 0
	v_mul_f32_e32 v24, 0x45800000, v2
	v_cndmask_b32_e32 v2, v2, v24, vcc
	v_pk_mul_f32 v[26:27], v[32:33], v[2:3] op_sel_hi:[1,0]
	v_pk_mul_f32 v[24:25], v[34:35], v[2:3] op_sel_hi:[1,0]
	s_waitcnt vmcnt(2)
; __device__ __forceinline__ unsigned pk2(float lo, float hi) { return f2bf(lo) | (f2bf(hi) << 16); }
; __device__ __forceinline__ void rowwise_phase(const Params& P, int mrows, bool first, int l_post, int j_post, int gate_idx, float coef, bool final_, int l_pre, int j_pre, int shift_idx, int scale_idx) {
;     ...
; #pragma unroll
;             for (int j = 0; j < 8; ++j) { const int c = 4 * lane + 256 * j; const f32x4 g4 = *(const f32x4*)(gp + c), sh = *(const f32x4*)(mb + shift_idx * DM + c), scl = *(const f32x4*)(mb + scale_idx * DM + c);
;                 const f32x4 h = (xv[j] * rs) * g4 * (scl + 1.f) + sh; u32x2 w; w.x = pk2(h.x, h.y); w.y = pk2(h.z, h.w); *(u32x2*)(hr + c) = w; }
	v_pk_mul_f32 v[12:13], v[12:13], v[26:27]
	s_waitcnt vmcnt(0)
	v_pk_add_f32 v[26:27], v[48:49], 1.0 op_sel_hi:[1,0]
	v_pk_mul_f32 v[14:15], v[14:15], v[24:25]
	v_pk_add_f32 v[24:25], v[50:51], 1.0 op_sel_hi:[1,0]
	v_pk_fma_f32 v[12:13], v[26:27], v[12:13], v[28:29]
	v_pk_fma_f32 v[14:15], v[24:25], v[14:15], v[30:31]
	v_bfe_u32 v24, v12, 16, 1
	v_add3_u32 v12, v12, v24, s71
	v_bfe_u32 v24, v13, 16, 1
	v_lshrrev_b32_e32 v12, 16, v12
	v_add3_u32 v13, v13, v24, s71
	v_and_or_b32 v24, v13, s70, v12
	v_bfe_u32 v12, v14, 16, 1
	v_add3_u32 v12, v14, v12, s71
	v_bfe_u32 v13, v15, 16, 1
	v_lshrrev_b32_e32 v12, 16, v12
	v_add3_u32 v13, v15, v13, s71
	v_and_or_b32 v25, v13, s70, v12
	v_lshl_add_u64 v[12:13], v[78:79], 0, s[22:23]
	global_store_dwordx2 v[12:13], v[24:25], off
	global_load_dwordx4 v[196:199], v[66:67], off offset:1024
	global_load_dwordx4 v[200:203], v111, s[20:21]
	global_load_dwordx4 v[204:207], v111, s[18:19]
	global_load_dwordx4 v[208:211], v[66:67], off offset:2048
	global_load_dwordx4 v[212:215], v112, s[20:21]
	global_load_dwordx4 v[216:219], v112, s[18:19]
	global_load_dwordx4 v[220:223], v[66:67], off offset:3072
	global_load_dwordx4 v[224:227], v113, s[20:21]
	global_load_dwordx4 v[228:231], v113, s[18:19]
	global_load_dwordx4 v[232:235], v[68:69], off
	global_load_dwordx4 v[236:239], v107, s[20:21]
	global_load_dwordx4 v[240:243], v107, s[18:19]
	s_nop 0
	v_pk_mul_f32 v[40:41], v[40:41], v[2:3] op_sel_hi:[1,0]
	v_pk_mul_f32 v[14:15], v[42:43], v[2:3] op_sel_hi:[1,0]
	v_pk_mul_f32 v[36:37], v[36:37], v[2:3] op_sel_hi:[1,0]
	v_pk_mul_f32 v[20:21], v[20:21], v[2:3] op_sel_hi:[1,0]
	v_pk_mul_f32 v[16:17], v[16:17], v[2:3] op_sel_hi:[1,0]
	v_pk_mul_f32 v[10:11], v[10:11], v[2:3] op_sel_hi:[1,0]
	v_pk_mul_f32 v[8:9], v[8:9], v[2:3] op_sel_hi:[1,0]
	v_pk_mul_f32 v[6:7], v[6:7], v[2:3] op_sel_hi:[1,0]
	v_pk_mul_f32 v[4:5], v[4:5], v[2:3] op_sel_hi:[1,0]
	s_waitcnt vmcnt(11)
	v_pk_mul_f32 v[24:25], v[196:197], v[40:41]
	s_waitcnt vmcnt(10)
	v_pk_add_f32 v[28:29], v[200:201], 1.0 op_sel_hi:[1,0]
	v_pk_mul_f32 v[14:15], v[198:199], v[14:15]
	v_pk_add_f32 v[26:27], v[202:203], 1.0 op_sel_hi:[1,0]
	s_waitcnt vmcnt(9)
	v_pk_fma_f32 v[24:25], v[28:29], v[24:25], v[204:205]
	v_pk_fma_f32 v[14:15], v[26:27], v[14:15], v[206:207]
	v_bfe_u32 v26, v24, 16, 1
	v_add3_u32 v24, v24, v26, s71
	v_bfe_u32 v26, v25, 16, 1
	v_lshrrev_b32_e32 v24, 16, v24
	v_add3_u32 v25, v25, v26, s71
	v_and_or_b32 v24, v25, s70, v24
	v_bfe_u32 v25, v14, 16, 1
	v_add3_u32 v14, v14, v25, s71
	v_bfe_u32 v25, v15, 16, 1
	v_lshrrev_b32_e32 v14, 16, v14
	v_add3_u32 v15, v15, v25, s71
	v_and_or_b32 v25, v15, s70, v14
	global_store_dwordx2 v[12:13], v[24:25], off offset:512
	global_load_dwordx4 v[196:199], v[70:71], off
	global_load_dwordx4 v[200:203], v108, s[20:21]
	global_load_dwordx4 v[204:207], v108, s[18:19]
	s_nop 0
	v_pk_mul_f32 v[14:15], v[38:39], v[2:3] op_sel_hi:[1,0]
	s_waitcnt vmcnt(12)
	v_pk_mul_f32 v[24:25], v[208:209], v[36:37]
	s_waitcnt vmcnt(11)
	v_pk_add_f32 v[28:29], v[212:213], 1.0 op_sel_hi:[1,0]
	v_pk_mul_f32 v[14:15], v[210:211], v[14:15]
	v_pk_add_f32 v[26:27], v[214:215], 1.0 op_sel_hi:[1,0]
	s_waitcnt vmcnt(10)
	v_pk_fma_f32 v[24:25], v[28:29], v[24:25], v[216:217]
	v_pk_fma_f32 v[14:15], v[26:27], v[14:15], v[218:219]
	v_bfe_u32 v26, v24, 16, 1
	v_add3_u32 v24, v24, v26, s71
	v_bfe_u32 v26, v25, 16, 1
	v_lshrrev_b32_e32 v24, 16, v24
	v_add3_u32 v25, v25, v26, s71
	v_and_or_b32 v24, v25, s70, v24
	v_bfe_u32 v25, v14, 16, 1
	v_add3_u32 v14, v14, v25, s71
	v_bfe_u32 v25, v15, 16, 1
	v_lshrrev_b32_e32 v14, 16, v14
	v_add3_u32 v15, v15, v25, s71
	v_and_or_b32 v25, v15, s70, v14
	global_store_dwordx2 v[12:13], v[24:25], off offset:1024
	global_load_dwordx4 v[208:211], v[72:73], off
	global_load_dwordx4 v[212:215], v109, s[20:21]
	global_load_dwordx4 v[216:219], v109, s[18:19]
	s_nop 0
	v_pk_mul_f32 v[14:15], v[46:47], v[2:3] op_sel_hi:[1,0]
	v_pk_mul_f32 v[36:37], v[44:45], v[2:3] op_sel_hi:[1,0]
	s_waitcnt vmcnt(13)
	v_pk_mul_f32 v[14:15], v[14:15], v[222:223]
	v_pk_mul_f32 v[24:25], v[36:37], v[220:221]
	s_waitcnt vmcnt(12)
; __device__ __forceinline__ unsigned pk2(float lo, float hi) { return f2bf(lo) | (f2bf(hi) << 16); }
; __device__ __forceinline__ void rowwise_phase(const Params& P, int mrows, bool first, int l_post, int j_post, int gate_idx, float coef, bool final_, int l_pre, int j_pre, int shift_idx, int scale_idx) {
;     ...
; #pragma unroll
;             for (int j = 0; j < 8; ++j) { const int c = 4 * lane + 256 * j; const f32x4 g4 = *(const f32x4*)(gp + c), sh = *(const f32x4*)(mb + shift_idx * DM + c), scl = *(const f32x4*)(mb + scale_idx * DM + c);
;                 const f32x4 h = (xv[j] * rs) * g4 * (scl + 1.f) + sh; u32x2 w; w.x = pk2(h.x, h.y); w.y = pk2(h.z, h.w); *(u32x2*)(hr + c) = w; }
	v_pk_add_f32 v[26:27], v[226:227], 1.0 op_sel_hi:[1,0]
	v_pk_add_f32 v[28:29], v[224:225], 1.0 op_sel_hi:[1,0]
	s_waitcnt vmcnt(11)
	v_pk_fma_f32 v[14:15], v[14:15], v[26:27], v[230:231]
	v_pk_fma_f32 v[24:25], v[24:25], v[28:29], v[228:229]
	v_bfe_u32 v28, v14, 16, 1
	v_bfe_u32 v26, v24, 16, 1
	v_bfe_u32 v27, v25, 16, 1
	v_bfe_u32 v29, v15, 16, 1
	v_add3_u32 v24, v24, v26, s71
	v_add3_u32 v14, v14, v28, s71
	v_add3_u32 v25, v25, v27, s71
	v_add3_u32 v15, v15, v29, s71
	v_lshrrev_b32_e32 v24, 16, v24
	v_lshrrev_b32_e32 v26, 16, v14
	v_and_or_b32 v14, v25, s70, v24
	v_and_or_b32 v15, v15, s70, v26
	global_store_dwordx2 v[12:13], v[14:15], off offset:1536
	global_load_dwordx4 v[220:223], v[74:75], off
	global_load_dwordx4 v[224:227], v110, s[20:21]
	global_load_dwordx4 v[228:231], v110, s[18:19]
	v_pk_mul_f32 v[14:15], v[22:23], v[2:3] op_sel_hi:[1,0]
	s_waitcnt vmcnt(14)
	v_pk_mul_f32 v[20:21], v[20:21], v[232:233]
	v_pk_mul_f32 v[14:15], v[14:15], v[234:235]
	s_waitcnt vmcnt(13)
	v_pk_add_f32 v[22:23], v[238:239], 1.0 op_sel_hi:[1,0]
	v_pk_add_f32 v[24:25], v[236:237], 1.0 op_sel_hi:[1,0]
	s_waitcnt vmcnt(12)
	v_pk_fma_f32 v[14:15], v[14:15], v[22:23], v[242:243]
	v_pk_fma_f32 v[20:21], v[20:21], v[24:25], v[240:241]
	v_bfe_u32 v24, v14, 16, 1
	v_bfe_u32 v22, v20, 16, 1
	v_bfe_u32 v23, v21, 16, 1
	v_bfe_u32 v25, v15, 16, 1
	v_add3_u32 v20, v20, v22, s71
	v_add3_u32 v14, v14, v24, s71
	v_add3_u32 v21, v21, v23, s71
	v_add3_u32 v15, v15, v25, s71
	v_lshrrev_b32_e32 v20, 16, v20
	v_lshrrev_b32_e32 v22, 16, v14
	v_and_or_b32 v14, v21, s70, v20
	v_and_or_b32 v15, v15, s70, v22
	global_store_dwordx2 v[12:13], v[14:15], off offset:2048
	v_pk_mul_f32 v[14:15], v[18:19], v[2:3] op_sel_hi:[1,0]
	s_waitcnt vmcnt(11)
	v_pk_mul_f32 v[16:17], v[16:17], v[196:197]
	v_pk_mul_f32 v[14:15], v[14:15], v[198:199]
	s_waitcnt vmcnt(10)
	v_pk_add_f32 v[18:19], v[202:203], 1.0 op_sel_hi:[1,0]
	v_pk_add_f32 v[20:21], v[200:201], 1.0 op_sel_hi:[1,0]
	s_waitcnt vmcnt(9)
	v_pk_fma_f32 v[14:15], v[14:15], v[18:19], v[206:207]
	v_pk_fma_f32 v[16:17], v[16:17], v[20:21], v[204:205]
	v_bfe_u32 v20, v14, 16, 1
	v_bfe_u32 v18, v16, 16, 1
	v_bfe_u32 v19, v17, 16, 1
	v_bfe_u32 v21, v15, 16, 1
	v_add3_u32 v16, v16, v18, s71
	v_add3_u32 v14, v14, v20, s71
	v_add3_u32 v17, v17, v19, s71
	v_add3_u32 v15, v15, v21, s71
	v_lshrrev_b32_e32 v16, 16, v16
	v_lshrrev_b32_e32 v18, 16, v14
	v_and_or_b32 v14, v17, s70, v16
	v_and_or_b32 v15, v15, s70, v18
	global_store_dwordx2 v[12:13], v[14:15], off offset:2560
	s_nop 0
	s_waitcnt vmcnt(8)
	v_pk_mul_f32 v[8:9], v[8:9], v[208:209]
	v_pk_mul_f32 v[10:11], v[10:11], v[210:211]
	s_waitcnt vmcnt(7)
	v_pk_add_f32 v[14:15], v[214:215], 1.0 op_sel_hi:[1,0]
	v_pk_add_f32 v[16:17], v[212:213], 1.0 op_sel_hi:[1,0]
	s_waitcnt vmcnt(6)
	v_pk_fma_f32 v[10:11], v[10:11], v[14:15], v[218:219]
	v_pk_fma_f32 v[8:9], v[8:9], v[16:17], v[216:217]
	v_bfe_u32 v16, v10, 16, 1
	v_bfe_u32 v14, v8, 16, 1
	v_bfe_u32 v15, v9, 16, 1
	v_bfe_u32 v17, v11, 16, 1
	v_add3_u32 v8, v8, v14, s71
	v_add3_u32 v10, v10, v16, s71
	v_add3_u32 v9, v9, v15, s71
	v_add3_u32 v11, v11, v17, s71
	v_lshrrev_b32_e32 v8, 16, v8
	v_lshrrev_b32_e32 v10, 16, v10
	v_and_or_b32 v8, v9, s70, v8
	v_and_or_b32 v9, v11, s70, v10
	global_store_dwordx2 v[12:13], v[8:9], off offset:3072
	s_nop 0
	s_waitcnt vmcnt(5)
	v_pk_mul_f32 v[4:5], v[4:5], v[220:221]
	v_pk_mul_f32 v[6:7], v[6:7], v[222:223]
	s_waitcnt vmcnt(4)
	v_pk_add_f32 v[8:9], v[226:227], 1.0 op_sel_hi:[1,0]
	v_pk_add_f32 v[10:11], v[224:225], 1.0 op_sel_hi:[1,0]
	s_waitcnt vmcnt(3)
	v_pk_fma_f32 v[6:7], v[6:7], v[8:9], v[230:231]
	v_pk_fma_f32 v[4:5], v[4:5], v[10:11], v[228:229]
	v_bfe_u32 v9, v6, 16, 1
	v_bfe_u32 v2, v4, 16, 1
	v_bfe_u32 v8, v5, 16, 1
	v_bfe_u32 v10, v7, 16, 1
	v_add3_u32 v2, v4, v2, s71
	v_add3_u32 v4, v5, v8, s71
	v_add3_u32 v5, v6, v9, s71
	v_add3_u32 v6, v7, v10, s71
	v_lshrrev_b32_e32 v2, 16, v2
	v_lshrrev_b32_e32 v5, 16, v5
	v_and_or_b32 v4, v4, s70, v2
	v_and_or_b32 v5, v6, s70, v5
	global_store_dwordx2 v[12:13], v[4:5], off offset:3584
	s_cbranch_scc1 .LBB0_294

; __device__ __forceinline__ f32x4 ld_bf4(const bf16* p) { const u32x2 w = *(const u32x2*)p; return (f32x4){__builtin_bit_cast(float, w.x << 16), __builtin_bit_cast(float, w.x & 0xffff0000u), __builtin_bit_cast(float, w.y << 16), __builtin_bit_cast(float, w.y & 0xffff0000u)}; }
; __device__ __forceinline__ void rowwise_phase(const Params& P, int mrows, bool first, int l_post, int j_post, int gate_idx, float coef, bool final_, int l_pre, int j_pre, int shift_idx, int scale_idx) {
;     ...
;                 const bf16* pr = (const bf16*)(P.ws + WS_YD) + (size_t)(row - MLAT) * DM;
; #pragma unroll
;                 for (int j = 0; j < 8; ++j) yv[j] = ld_bf4(pr + 4 * lane + 256 * j);
;                 for (int ks = 1; ks < 8; ++ks) {
; #pragma unroll
;                     for (int j = 0; j < 8; ++j) yv[j] += ld_bf4(pr + (size_t)ks * MCTX * DM + 4 * lane + 256 * j);
;                 }
.LBB0_290:
	s_mov_b64 s[24:25], -1
	s_and_b64 vcc, exec, s[22:23]
	s_cbranch_vccz .LBB0_292
	s_add_i32 s58, s6, 0xffffe000
	s_lshl_b64 s[24:25], s[58:59], 12
	s_add_u32 s24, s24, s94
	s_addc_u32 s25, s25, s95
	s_add_u32 s24, s24, 0x34f00000
	s_addc_u32 s25, s25, 0
	v_lshlrev_b32_e32 v52, 3, v174
	global_load_dwordx2 v[6:7], v52, s[24:25] offset:0
	global_load_dwordx2 v[22:23], v52, s[24:25] offset:512
	global_load_dwordx2 v[30:31], v52, s[24:25] offset:1024
	global_load_dwordx2 v[14:15], v52, s[24:25] offset:1536
	global_load_dwordx2 v[10:11], v52, s[24:25] offset:2048
	global_load_dwordx2 v[18:19], v52, s[24:25] offset:2560
	global_load_dwordx2 v[26:27], v52, s[24:25] offset:3072
	global_load_dwordx2 v[34:35], v52, s[24:25] offset:3584
	s_add_u32 s24, s24, 0x400000
	s_addc_u32 s25, s25, 0
	global_load_dwordx2 v[36:37], v52, s[24:25] offset:0
	global_load_dwordx2 v[38:39], v52, s[24:25] offset:512
	global_load_dwordx2 v[40:41], v52, s[24:25] offset:1024
	global_load_dwordx2 v[42:43], v52, s[24:25] offset:1536
	global_load_dwordx2 v[44:45], v52, s[24:25] offset:2048
	global_load_dwordx2 v[46:47], v52, s[24:25] offset:2560
	global_load_dwordx2 v[48:49], v52, s[24:25] offset:3072
	global_load_dwordx2 v[50:51], v52, s[24:25] offset:3584
	s_waitcnt vmcnt(15)
	v_lshlrev_b32_e32 v4, 16, v6
	v_and_b32_e32 v5, 0xffff0000, v6
	v_lshlrev_b32_e32 v6, 16, v7
	v_and_b32_e32 v7, 0xffff0000, v7
	s_waitcnt vmcnt(14)
	v_lshlrev_b32_e32 v20, 16, v22
	v_and_b32_e32 v21, 0xffff0000, v22
	v_lshlrev_b32_e32 v22, 16, v23
	v_and_b32_e32 v23, 0xffff0000, v23
	s_waitcnt vmcnt(13)
	v_lshlrev_b32_e32 v28, 16, v30
	v_and_b32_e32 v29, 0xffff0000, v30
	v_lshlrev_b32_e32 v30, 16, v31
	v_and_b32_e32 v31, 0xffff0000, v31
	s_waitcnt vmcnt(12)
	v_lshlrev_b32_e32 v12, 16, v14
	v_and_b32_e32 v13, 0xffff0000, v14
	v_lshlrev_b32_e32 v14, 16, v15
	v_and_b32_e32 v15, 0xffff0000, v15
	s_waitcnt vmcnt(11)
	v_lshlrev_b32_e32 v8, 16, v10
	v_and_b32_e32 v9, 0xffff0000, v10
	v_lshlrev_b32_e32 v10, 16, v11
	v_and_b32_e32 v11, 0xffff0000, v11
	s_waitcnt vmcnt(10)
	v_lshlrev_b32_e32 v16, 16, v18
	v_and_b32_e32 v17, 0xffff0000, v18
	v_lshlrev_b32_e32 v18, 16, v19
	v_and_b32_e32 v19, 0xffff0000, v19
	s_waitcnt vmcnt(9)
	v_lshlrev_b32_e32 v24, 16, v26
	v_and_b32_e32 v25, 0xffff0000, v26
	v_lshlrev_b32_e32 v26, 16, v27
	v_and_b32_e32 v27, 0xffff0000, v27
	s_waitcnt vmcnt(8)
	v_lshlrev_b32_e32 v32, 16, v34
	v_and_b32_e32 v33, 0xffff0000, v34
	v_lshlrev_b32_e32 v34, 16, v35
	v_and_b32_e32 v35, 0xffff0000, v35
	s_waitcnt vmcnt(7)
	v_lshlrev_b32_e32 v52, 16, v36
	v_and_b32_e32 v53, 0xffff0000, v36
	v_pk_add_f32 v[4:5], v[4:5], v[52:53]
	v_lshlrev_b32_e32 v52, 16, v37
	v_and_b32_e32 v53, 0xffff0000, v37
	v_pk_add_f32 v[6:7], v[6:7], v[52:53]
	s_waitcnt vmcnt(6)
	v_lshlrev_b32_e32 v52, 16, v38
	v_and_b32_e32 v53, 0xffff0000, v38
	v_pk_add_f32 v[20:21], v[20:21], v[52:53]
	v_lshlrev_b32_e32 v52, 16, v39
	v_and_b32_e32 v53, 0xffff0000, v39
	v_pk_add_f32 v[22:23], v[22:23], v[52:53]
	s_waitcnt vmcnt(5)
	v_lshlrev_b32_e32 v52, 16, v40
	v_and_b32_e32 v53, 0xffff0000, v40
	v_pk_add_f32 v[28:29], v[28:29], v[52:53]
	v_lshlrev_b32_e32 v52, 16, v41
	v_and_b32_e32 v53, 0xffff0000, v41
	v_pk_add_f32 v[30:31], v[30:31], v[52:53]
	s_waitcnt vmcnt(4)
	v_lshlrev_b32_e32 v52, 16, v42
	v_and_b32_e32 v53, 0xffff0000, v42
	v_pk_add_f32 v[12:13], v[12:13], v[52:53]
	v_lshlrev_b32_e32 v52, 16, v43
	v_and_b32_e32 v53, 0xffff0000, v43
	v_pk_add_f32 v[14:15], v[14:15], v[52:53]
	s_waitcnt vmcnt(3)
	v_lshlrev_b32_e32 v52, 16, v44
	v_and_b32_e32 v53, 0xffff0000, v44
	v_pk_add_f32 v[8:9], v[8:9], v[52:53]
	v_lshlrev_b32_e32 v52, 16, v45
	v_and_b32_e32 v53, 0xffff0000, v45
	v_pk_add_f32 v[10:11], v[10:11], v[52:53]
	s_waitcnt vmcnt(2)
	v_lshlrev_b32_e32 v52, 16, v46
	v_and_b32_e32 v53, 0xffff0000, v46
	v_pk_add_f32 v[16:17], v[16:17], v[52:53]
	v_lshlrev_b32_e32 v52, 16, v47
	v_and_b32_e32 v53, 0xffff0000, v47
	v_pk_add_f32 v[18:19], v[18:19], v[52:53]
	s_waitcnt vmcnt(1)
	v_lshlrev_b32_e32 v52, 16, v48
	v_and_b32_e32 v53, 0xffff0000, v48
	v_pk_add_f32 v[24:25], v[24:25], v[52:53]
	v_lshlrev_b32_e32 v52, 16, v49
	v_and_b32_e32 v53, 0xffff0000, v49
	v_pk_add_f32 v[26:27], v[26:27], v[52:53]
	s_waitcnt vmcnt(0)
	v_lshlrev_b32_e32 v52, 16, v50
	v_and_b32_e32 v53, 0xffff0000, v50
	v_pk_add_f32 v[32:33], v[32:33], v[52:53]
	v_lshlrev_b32_e32 v52, 16, v51
	v_and_b32_e32 v53, 0xffff0000, v51
	v_pk_add_f32 v[34:35], v[34:35], v[52:53]
	s_add_u32 s24, s24, 0x400000
	s_addc_u32 s25, s25, 0
	v_lshlrev_b32_e32 v52, 3, v174
	global_load_dwordx2 v[36:37], v52, s[24:25] offset:0
	global_load_dwordx2 v[38:39], v52, s[24:25] offset:512
	global_load_dwordx2 v[40:41], v52, s[24:25] offset:1024
	global_load_dwordx2 v[42:43], v52, s[24:25] offset:1536
	global_load_dwordx2 v[44:45], v52, s[24:25] offset:2048
	global_load_dwordx2 v[46:47], v52, s[24:25] offset:2560
	global_load_dwordx2 v[48:49], v52, s[24:25] offset:3072
	global_load_dwordx2 v[50:51], v52, s[24:25] offset:3584
	s_waitcnt vmcnt(7)
	v_lshlrev_b32_e32 v52, 16, v36
	v_and_b32_e32 v53, 0xffff0000, v36
	v_pk_add_f32 v[4:5], v[4:5], v[52:53]
	v_lshlrev_b32_e32 v52, 16, v37
	v_and_b32_e32 v53, 0xffff0000, v37
	v_pk_add_f32 v[6:7], v[6:7], v[52:53]
	s_waitcnt vmcnt(6)
	v_lshlrev_b32_e32 v52, 16, v38
	v_and_b32_e32 v53, 0xffff0000, v38
	v_pk_add_f32 v[20:21], v[20:21], v[52:53]
	v_lshlrev_b32_e32 v52, 16, v39
	v_and_b32_e32 v53, 0xffff0000, v39
	v_pk_add_f32 v[22:23], v[22:23], v[52:53]
	s_waitcnt vmcnt(5)
	v_lshlrev_b32_e32 v52, 16, v40
	v_and_b32_e32 v53, 0xffff0000, v40
	v_pk_add_f32 v[28:29], v[28:29], v[52:53]
	v_lshlrev_b32_e32 v52, 16, v41
	v_and_b32_e32 v53, 0xffff0000, v41
	v_pk_add_f32 v[30:31], v[30:31], v[52:53]
	s_waitcnt vmcnt(4)
; __device__ __forceinline__ f32x4 ld_bf4(const bf16* p) { const u32x2 w = *(const u32x2*)p; return (f32x4){__builtin_bit_cast(float, w.x << 16), __builtin_bit_cast(float, w.x & 0xffff0000u), __builtin_bit_cast(float, w.y << 16), __builtin_bit_cast(float, w.y & 0xffff0000u)}; }
; __device__ __forceinline__ void rowwise_phase(const Params& P, int mrows, bool first, int l_post, int j_post, int gate_idx, float coef, bool final_, int l_pre, int j_pre, int shift_idx, int scale_idx) {
;     ...
;                 for (int ks = 1; ks < 8; ++ks) {
; #pragma unroll
;                     for (int j = 0; j < 8; ++j) yv[j] += ld_bf4(pr + (size_t)ks * MCTX * DM + 4 * lane + 256 * j);
;                 }
	v_lshlrev_b32_e32 v52, 16, v42
	v_and_b32_e32 v53, 0xffff0000, v42
	v_pk_add_f32 v[12:13], v[12:13], v[52:53]
	v_lshlrev_b32_e32 v52, 16, v43
	v_and_b32_e32 v53, 0xffff0000, v43
	v_pk_add_f32 v[14:15], v[14:15], v[52:53]
	s_waitcnt vmcnt(3)
	v_lshlrev_b32_e32 v52, 16, v44
	v_and_b32_e32 v53, 0xffff0000, v44
	v_pk_add_f32 v[8:9], v[8:9], v[52:53]
	v_lshlrev_b32_e32 v52, 16, v45
	v_and_b32_e32 v53, 0xffff0000, v45
	v_pk_add_f32 v[10:11], v[10:11], v[52:53]
	s_waitcnt vmcnt(2)
	v_lshlrev_b32_e32 v52, 16, v46
	v_and_b32_e32 v53, 0xffff0000, v46
	v_pk_add_f32 v[16:17], v[16:17], v[52:53]
	v_lshlrev_b32_e32 v52, 16, v47
	v_and_b32_e32 v53, 0xffff0000, v47
	v_pk_add_f32 v[18:19], v[18:19], v[52:53]
	s_waitcnt vmcnt(1)
	v_lshlrev_b32_e32 v52, 16, v48
	v_and_b32_e32 v53, 0xffff0000, v48
	v_pk_add_f32 v[24:25], v[24:25], v[52:53]
	v_lshlrev_b32_e32 v52, 16, v49
	v_and_b32_e32 v53, 0xffff0000, v49
	v_pk_add_f32 v[26:27], v[26:27], v[52:53]
	s_waitcnt vmcnt(0)
	v_lshlrev_b32_e32 v52, 16, v50
	v_and_b32_e32 v53, 0xffff0000, v50
	v_pk_add_f32 v[32:33], v[32:33], v[52:53]
	v_lshlrev_b32_e32 v52, 16, v51
	v_and_b32_e32 v53, 0xffff0000, v51
	v_pk_add_f32 v[34:35], v[34:35], v[52:53]
	s_add_u32 s24, s24, 0x400000
	s_addc_u32 s25, s25, 0
	v_lshlrev_b32_e32 v52, 3, v174
	global_load_dwordx2 v[36:37], v52, s[24:25] offset:0
	global_load_dwordx2 v[38:39], v52, s[24:25] offset:512
	global_load_dwordx2 v[40:41], v52, s[24:25] offset:1024
	global_load_dwordx2 v[42:43], v52, s[24:25] offset:1536
	global_load_dwordx2 v[44:45], v52, s[24:25] offset:2048
	global_load_dwordx2 v[46:47], v52, s[24:25] offset:2560
	global_load_dwordx2 v[48:49], v52, s[24:25] offset:3072
	global_load_dwordx2 v[50:51], v52, s[24:25] offset:3584
	s_waitcnt vmcnt(7)
	v_lshlrev_b32_e32 v52, 16, v36
	v_and_b32_e32 v53, 0xffff0000, v36
	v_pk_add_f32 v[4:5], v[4:5], v[52:53]
	v_lshlrev_b32_e32 v52, 16, v37
	v_and_b32_e32 v53, 0xffff0000, v37
	v_pk_add_f32 v[6:7], v[6:7], v[52:53]
	s_waitcnt vmcnt(6)
	v_lshlrev_b32_e32 v52, 16, v38
	v_and_b32_e32 v53, 0xffff0000, v38
	v_pk_add_f32 v[20:21], v[20:21], v[52:53]
	v_lshlrev_b32_e32 v52, 16, v39
	v_and_b32_e32 v53, 0xffff0000, v39
	v_pk_add_f32 v[22:23], v[22:23], v[52:53]
	s_waitcnt vmcnt(5)
	v_lshlrev_b32_e32 v52, 16, v40
	v_and_b32_e32 v53, 0xffff0000, v40
	v_pk_add_f32 v[28:29], v[28:29], v[52:53]
	v_lshlrev_b32_e32 v52, 16, v41
	v_and_b32_e32 v53, 0xffff0000, v41
	v_pk_add_f32 v[30:31], v[30:31], v[52:53]
	s_waitcnt vmcnt(4)
	v_lshlrev_b32_e32 v52, 16, v42
	v_and_b32_e32 v53, 0xffff0000, v42
	v_pk_add_f32 v[12:13], v[12:13], v[52:53]
	v_lshlrev_b32_e32 v52, 16, v43
	v_and_b32_e32 v53, 0xffff0000, v43
	v_pk_add_f32 v[14:15], v[14:15], v[52:53]
	s_waitcnt vmcnt(3)
	v_lshlrev_b32_e32 v52, 16, v44
	v_and_b32_e32 v53, 0xffff0000, v44
	v_pk_add_f32 v[8:9], v[8:9], v[52:53]
	v_lshlrev_b32_e32 v52, 16, v45
	v_and_b32_e32 v53, 0xffff0000, v45
	v_pk_add_f32 v[10:11], v[10:11], v[52:53]
	s_waitcnt vmcnt(2)
	v_lshlrev_b32_e32 v52, 16, v46
	v_and_b32_e32 v53, 0xffff0000, v46
	v_pk_add_f32 v[16:17], v[16:17], v[52:53]
	v_lshlrev_b32_e32 v52, 16, v47
	v_and_b32_e32 v53, 0xffff0000, v47
	v_pk_add_f32 v[18:19], v[18:19], v[52:53]
	s_waitcnt vmcnt(1)
	v_lshlrev_b32_e32 v52, 16, v48
	v_and_b32_e32 v53, 0xffff0000, v48
	v_pk_add_f32 v[24:25], v[24:25], v[52:53]
	v_lshlrev_b32_e32 v52, 16, v49
	v_and_b32_e32 v53, 0xffff0000, v49
	v_pk_add_f32 v[26:27], v[26:27], v[52:53]
	s_waitcnt vmcnt(0)
	v_lshlrev_b32_e32 v52, 16, v50
	v_and_b32_e32 v53, 0xffff0000, v50
	v_pk_add_f32 v[32:33], v[32:33], v[52:53]
	v_lshlrev_b32_e32 v52, 16, v51
	v_and_b32_e32 v53, 0xffff0000, v51
	v_pk_add_f32 v[34:35], v[34:35], v[52:53]
	s_add_u32 s24, s24, 0x400000
	s_addc_u32 s25, s25, 0
	v_lshlrev_b32_e32 v52, 3, v174
	global_load_dwordx2 v[36:37], v52, s[24:25] offset:0
	global_load_dwordx2 v[38:39], v52, s[24:25] offset:512
	global_load_dwordx2 v[40:41], v52, s[24:25] offset:1024
	global_load_dwordx2 v[42:43], v52, s[24:25] offset:1536
	global_load_dwordx2 v[44:45], v52, s[24:25] offset:2048
	global_load_dwordx2 v[46:47], v52, s[24:25] offset:2560
	global_load_dwordx2 v[48:49], v52, s[24:25] offset:3072
	global_load_dwordx2 v[50:51], v52, s[24:25] offset:3584
	s_waitcnt vmcnt(7)
	v_lshlrev_b32_e32 v52, 16, v36
	v_and_b32_e32 v53, 0xffff0000, v36
	v_pk_add_f32 v[4:5], v[4:5], v[52:53]
	v_lshlrev_b32_e32 v52, 16, v37
	v_and_b32_e32 v53, 0xffff0000, v37
	v_pk_add_f32 v[6:7], v[6:7], v[52:53]
	s_waitcnt vmcnt(6)
	v_lshlrev_b32_e32 v52, 16, v38
	v_and_b32_e32 v53, 0xffff0000, v38
	v_pk_add_f32 v[20:21], v[20:21], v[52:53]
	v_lshlrev_b32_e32 v52, 16, v39
	v_and_b32_e32 v53, 0xffff0000, v39
	v_pk_add_f32 v[22:23], v[22:23], v[52:53]
	s_waitcnt vmcnt(5)
	v_lshlrev_b32_e32 v52, 16, v40
	v_and_b32_e32 v53, 0xffff0000, v40
	v_pk_add_f32 v[28:29], v[28:29], v[52:53]
	v_lshlrev_b32_e32 v52, 16, v41
	v_and_b32_e32 v53, 0xffff0000, v41
	v_pk_add_f32 v[30:31], v[30:31], v[52:53]
	s_waitcnt vmcnt(4)
	v_lshlrev_b32_e32 v52, 16, v42
	v_and_b32_e32 v53, 0xffff0000, v42
	v_pk_add_f32 v[12:13], v[12:13], v[52:53]
	v_lshlrev_b32_e32 v52, 16, v43
	v_and_b32_e32 v53, 0xffff0000, v43
	v_pk_add_f32 v[14:15], v[14:15], v[52:53]
	s_waitcnt vmcnt(3)
	v_lshlrev_b32_e32 v52, 16, v44
	v_and_b32_e32 v53, 0xffff0000, v44
	v_pk_add_f32 v[8:9], v[8:9], v[52:53]
	v_lshlrev_b32_e32 v52, 16, v45
	v_and_b32_e32 v53, 0xffff0000, v45
	v_pk_add_f32 v[10:11], v[10:11], v[52:53]
	s_waitcnt vmcnt(2)
	v_lshlrev_b32_e32 v52, 16, v46
	v_and_b32_e32 v53, 0xffff0000, v46
	v_pk_add_f32 v[16:17], v[16:17], v[52:53]
	v_lshlrev_b32_e32 v52, 16, v47
	v_and_b32_e32 v53, 0xffff0000, v47
	v_pk_add_f32 v[18:19], v[18:19], v[52:53]
	s_waitcnt vmcnt(1)
; __device__ __forceinline__ f32x4 ld_bf4(const bf16* p) { const u32x2 w = *(const u32x2*)p; return (f32x4){__builtin_bit_cast(float, w.x << 16), __builtin_bit_cast(float, w.x & 0xffff0000u), __builtin_bit_cast(float, w.y << 16), __builtin_bit_cast(float, w.y & 0xffff0000u)}; }
; __device__ __forceinline__ void rowwise_phase(const Params& P, int mrows, bool first, int l_post, int j_post, int gate_idx, float coef, bool final_, int l_pre, int j_pre, int shift_idx, int scale_idx) {
;     ...
;                 for (int ks = 1; ks < 8; ++ks) {
; #pragma unroll
;                     for (int j = 0; j < 8; ++j) yv[j] += ld_bf4(pr + (size_t)ks * MCTX * DM + 4 * lane + 256 * j);
;                 }
	v_lshlrev_b32_e32 v52, 16, v48
	v_and_b32_e32 v53, 0xffff0000, v48
	v_pk_add_f32 v[24:25], v[24:25], v[52:53]
	v_lshlrev_b32_e32 v52, 16, v49
	v_and_b32_e32 v53, 0xffff0000, v49
	v_pk_add_f32 v[26:27], v[26:27], v[52:53]
	s_waitcnt vmcnt(0)
	v_lshlrev_b32_e32 v52, 16, v50
	v_and_b32_e32 v53, 0xffff0000, v50
	v_pk_add_f32 v[32:33], v[32:33], v[52:53]
	v_lshlrev_b32_e32 v52, 16, v51
	v_and_b32_e32 v53, 0xffff0000, v51
	v_pk_add_f32 v[34:35], v[34:35], v[52:53]
	s_add_u32 s24, s24, 0x400000
	s_addc_u32 s25, s25, 0
	v_lshlrev_b32_e32 v52, 3, v174
	global_load_dwordx2 v[36:37], v52, s[24:25] offset:0
	global_load_dwordx2 v[38:39], v52, s[24:25] offset:512
	global_load_dwordx2 v[40:41], v52, s[24:25] offset:1024
	global_load_dwordx2 v[42:43], v52, s[24:25] offset:1536
	global_load_dwordx2 v[44:45], v52, s[24:25] offset:2048
	global_load_dwordx2 v[46:47], v52, s[24:25] offset:2560
	global_load_dwordx2 v[48:49], v52, s[24:25] offset:3072
	global_load_dwordx2 v[50:51], v52, s[24:25] offset:3584
	s_waitcnt vmcnt(7)
	v_lshlrev_b32_e32 v52, 16, v36
	v_and_b32_e32 v53, 0xffff0000, v36
	v_pk_add_f32 v[4:5], v[4:5], v[52:53]
	v_lshlrev_b32_e32 v52, 16, v37
	v_and_b32_e32 v53, 0xffff0000, v37
	v_pk_add_f32 v[6:7], v[6:7], v[52:53]
	s_waitcnt vmcnt(6)
	v_lshlrev_b32_e32 v52, 16, v38
	v_and_b32_e32 v53, 0xffff0000, v38
	v_pk_add_f32 v[20:21], v[20:21], v[52:53]
	v_lshlrev_b32_e32 v52, 16, v39
	v_and_b32_e32 v53, 0xffff0000, v39
	v_pk_add_f32 v[22:23], v[22:23], v[52:53]
	s_waitcnt vmcnt(5)
	v_lshlrev_b32_e32 v52, 16, v40
	v_and_b32_e32 v53, 0xffff0000, v40
	v_pk_add_f32 v[28:29], v[28:29], v[52:53]
	v_lshlrev_b32_e32 v52, 16, v41
	v_and_b32_e32 v53, 0xffff0000, v41
	v_pk_add_f32 v[30:31], v[30:31], v[52:53]
	s_waitcnt vmcnt(4)
	v_lshlrev_b32_e32 v52, 16, v42
	v_and_b32_e32 v53, 0xffff0000, v42
	v_pk_add_f32 v[12:13], v[12:13], v[52:53]
	v_lshlrev_b32_e32 v52, 16, v43
	v_and_b32_e32 v53, 0xffff0000, v43
	v_pk_add_f32 v[14:15], v[14:15], v[52:53]
	s_waitcnt vmcnt(3)
	v_lshlrev_b32_e32 v52, 16, v44
	v_and_b32_e32 v53, 0xffff0000, v44
	v_pk_add_f32 v[8:9], v[8:9], v[52:53]
	v_lshlrev_b32_e32 v52, 16, v45
	v_and_b32_e32 v53, 0xffff0000, v45
	v_pk_add_f32 v[10:11], v[10:11], v[52:53]
	s_waitcnt vmcnt(2)
	v_lshlrev_b32_e32 v52, 16, v46
	v_and_b32_e32 v53, 0xffff0000, v46
	v_pk_add_f32 v[16:17], v[16:17], v[52:53]
	v_lshlrev_b32_e32 v52, 16, v47
	v_and_b32_e32 v53, 0xffff0000, v47
	v_pk_add_f32 v[18:19], v[18:19], v[52:53]
	s_waitcnt vmcnt(1)
	v_lshlrev_b32_e32 v52, 16, v48
	v_and_b32_e32 v53, 0xffff0000, v48
	v_pk_add_f32 v[24:25], v[24:25], v[52:53]
	v_lshlrev_b32_e32 v52, 16, v49
	v_and_b32_e32 v53, 0xffff0000, v49
	v_pk_add_f32 v[26:27], v[26:27], v[52:53]
	s_waitcnt vmcnt(0)
	v_lshlrev_b32_e32 v52, 16, v50
	v_and_b32_e32 v53, 0xffff0000, v50
	v_pk_add_f32 v[32:33], v[32:33], v[52:53]
	v_lshlrev_b32_e32 v52, 16, v51
	v_and_b32_e32 v53, 0xffff0000, v51
	v_pk_add_f32 v[34:35], v[34:35], v[52:53]
	s_add_u32 s24, s24, 0x400000
	s_addc_u32 s25, s25, 0
	v_lshlrev_b32_e32 v52, 3, v174
	global_load_dwordx2 v[36:37], v52, s[24:25] offset:0
	global_load_dwordx2 v[38:39], v52, s[24:25] offset:512
	global_load_dwordx2 v[40:41], v52, s[24:25] offset:1024
	global_load_dwordx2 v[42:43], v52, s[24:25] offset:1536
	global_load_dwordx2 v[44:45], v52, s[24:25] offset:2048
	global_load_dwordx2 v[46:47], v52, s[24:25] offset:2560
	global_load_dwordx2 v[48:49], v52, s[24:25] offset:3072
	global_load_dwordx2 v[50:51], v52, s[24:25] offset:3584
	s_waitcnt vmcnt(7)
	v_lshlrev_b32_e32 v52, 16, v36
	v_and_b32_e32 v53, 0xffff0000, v36
	v_pk_add_f32 v[4:5], v[4:5], v[52:53]
	v_lshlrev_b32_e32 v52, 16, v37
	v_and_b32_e32 v53, 0xffff0000, v37
	v_pk_add_f32 v[6:7], v[6:7], v[52:53]
	s_waitcnt vmcnt(6)
	v_lshlrev_b32_e32 v52, 16, v38
	v_and_b32_e32 v53, 0xffff0000, v38
	v_pk_add_f32 v[20:21], v[20:21], v[52:53]
	v_lshlrev_b32_e32 v52, 16, v39
	v_and_b32_e32 v53, 0xffff0000, v39
	v_pk_add_f32 v[22:23], v[22:23], v[52:53]
	s_waitcnt vmcnt(5)
; __device__ __forceinline__ f32x4 ld_bf4(const bf16* p) { const u32x2 w = *(const u32x2*)p; return (f32x4){__builtin_bit_cast(float, w.x << 16), __builtin_bit_cast(float, w.x & 0xffff0000u), __builtin_bit_cast(float, w.y << 16), __builtin_bit_cast(float, w.y & 0xffff0000u)}; }
; __device__ __forceinline__ void rowwise_phase(const Params& P, int mrows, bool first, int l_post, int j_post, int gate_idx, float coef, bool final_, int l_pre, int j_pre, int shift_idx, int scale_idx) {
;     ...
;                 for (int ks = 1; ks < 8; ++ks) {
; #pragma unroll
;                     for (int j = 0; j < 8; ++j) yv[j] += ld_bf4(pr + (size_t)ks * MCTX * DM + 4 * lane + 256 * j);
;                 }
	v_lshlrev_b32_e32 v52, 16, v40
	v_and_b32_e32 v53, 0xffff0000, v40
	v_pk_add_f32 v[28:29], v[28:29], v[52:53]
	v_lshlrev_b32_e32 v52, 16, v41
	v_and_b32_e32 v53, 0xffff0000, v41
	v_pk_add_f32 v[30:31], v[30:31], v[52:53]
	s_waitcnt vmcnt(4)
	v_lshlrev_b32_e32 v52, 16, v42
	v_and_b32_e32 v53, 0xffff0000, v42
	v_pk_add_f32 v[12:13], v[12:13], v[52:53]
	v_lshlrev_b32_e32 v52, 16, v43
	v_and_b32_e32 v53, 0xffff0000, v43
	v_pk_add_f32 v[14:15], v[14:15], v[52:53]
	s_waitcnt vmcnt(3)
	v_lshlrev_b32_e32 v52, 16, v44
	v_and_b32_e32 v53, 0xffff0000, v44
	v_pk_add_f32 v[8:9], v[8:9], v[52:53]
	v_lshlrev_b32_e32 v52, 16, v45
	v_and_b32_e32 v53, 0xffff0000, v45
	v_pk_add_f32 v[10:11], v[10:11], v[52:53]
	s_waitcnt vmcnt(2)
	v_lshlrev_b32_e32 v52, 16, v46
	v_and_b32_e32 v53, 0xffff0000, v46
	v_pk_add_f32 v[16:17], v[16:17], v[52:53]
	v_lshlrev_b32_e32 v52, 16, v47
	v_and_b32_e32 v53, 0xffff0000, v47
	v_pk_add_f32 v[18:19], v[18:19], v[52:53]
	s_waitcnt vmcnt(1)
	v_lshlrev_b32_e32 v52, 16, v48
	v_and_b32_e32 v53, 0xffff0000, v48
	v_pk_add_f32 v[24:25], v[24:25], v[52:53]
	v_lshlrev_b32_e32 v52, 16, v49
	v_and_b32_e32 v53, 0xffff0000, v49
	v_pk_add_f32 v[26:27], v[26:27], v[52:53]
	s_waitcnt vmcnt(0)
	v_lshlrev_b32_e32 v52, 16, v50
	v_and_b32_e32 v53, 0xffff0000, v50
	v_pk_add_f32 v[32:33], v[32:33], v[52:53]
	v_lshlrev_b32_e32 v52, 16, v51
	v_and_b32_e32 v53, 0xffff0000, v51
	v_pk_add_f32 v[34:35], v[34:35], v[52:53]
	s_add_u32 s24, s24, 0x400000
	s_addc_u32 s25, s25, 0
	v_lshlrev_b32_e32 v52, 3, v174
	global_load_dwordx2 v[36:37], v52, s[24:25] offset:0
	global_load_dwordx2 v[38:39], v52, s[24:25] offset:512
	global_load_dwordx2 v[40:41], v52, s[24:25] offset:1024
	global_load_dwordx2 v[42:43], v52, s[24:25] offset:1536
	global_load_dwordx2 v[44:45], v52, s[24:25] offset:2048
	global_load_dwordx2 v[46:47], v52, s[24:25] offset:2560
	global_load_dwordx2 v[48:49], v52, s[24:25] offset:3072
	global_load_dwordx2 v[50:51], v52, s[24:25] offset:3584
	s_waitcnt vmcnt(7)
	v_lshlrev_b32_e32 v52, 16, v36
	v_and_b32_e32 v53, 0xffff0000, v36
	v_pk_add_f32 v[4:5], v[4:5], v[52:53]
	v_lshlrev_b32_e32 v52, 16, v37
	v_and_b32_e32 v53, 0xffff0000, v37
	v_pk_add_f32 v[6:7], v[6:7], v[52:53]
	s_waitcnt vmcnt(6)
	v_lshlrev_b32_e32 v52, 16, v38
	v_and_b32_e32 v53, 0xffff0000, v38
	v_pk_add_f32 v[20:21], v[20:21], v[52:53]
	v_lshlrev_b32_e32 v52, 16, v39
	v_and_b32_e32 v53, 0xffff0000, v39
	v_pk_add_f32 v[22:23], v[22:23], v[52:53]
	s_waitcnt vmcnt(5)
	v_lshlrev_b32_e32 v52, 16, v40
	v_and_b32_e32 v53, 0xffff0000, v40
	v_pk_add_f32 v[28:29], v[28:29], v[52:53]
	v_lshlrev_b32_e32 v52, 16, v41
	v_and_b32_e32 v53, 0xffff0000, v41
	v_pk_add_f32 v[30:31], v[30:31], v[52:53]
	s_waitcnt vmcnt(4)
	v_lshlrev_b32_e32 v52, 16, v42
	v_and_b32_e32 v53, 0xffff0000, v42
	v_pk_add_f32 v[12:13], v[12:13], v[52:53]
	v_lshlrev_b32_e32 v52, 16, v43
	v_and_b32_e32 v53, 0xffff0000, v43
	v_pk_add_f32 v[14:15], v[14:15], v[52:53]
	s_waitcnt vmcnt(3)
	v_lshlrev_b32_e32 v52, 16, v44
	v_and_b32_e32 v53, 0xffff0000, v44
	v_pk_add_f32 v[8:9], v[8:9], v[52:53]
	v_lshlrev_b32_e32 v52, 16, v45
	v_and_b32_e32 v53, 0xffff0000, v45
	v_pk_add_f32 v[10:11], v[10:11], v[52:53]
	s_waitcnt vmcnt(2)
	v_lshlrev_b32_e32 v52, 16, v46
	v_and_b32_e32 v53, 0xffff0000, v46
	v_pk_add_f32 v[16:17], v[16:17], v[52:53]
	v_lshlrev_b32_e32 v52, 16, v47
	v_and_b32_e32 v53, 0xffff0000, v47
	v_pk_add_f32 v[18:19], v[18:19], v[52:53]
	s_waitcnt vmcnt(1)
	v_lshlrev_b32_e32 v52, 16, v48
	v_and_b32_e32 v53, 0xffff0000, v48
	v_pk_add_f32 v[24:25], v[24:25], v[52:53]
	v_lshlrev_b32_e32 v52, 16, v49
	v_and_b32_e32 v53, 0xffff0000, v49
	v_pk_add_f32 v[26:27], v[26:27], v[52:53]
	s_waitcnt vmcnt(0)
	v_lshlrev_b32_e32 v52, 16, v50
	v_and_b32_e32 v53, 0xffff0000, v50
	v_pk_add_f32 v[32:33], v[32:33], v[52:53]
	v_lshlrev_b32_e32 v52, 16, v51
	v_and_b32_e32 v53, 0xffff0000, v51
	v_pk_add_f32 v[34:35], v[34:35], v[52:53]
	s_mov_b64 s[24:25], 0
	s_mov_b32 s22, s6
	s_mov_b32 s23, 0

; __device__ __forceinline__ void prologue_phase(const Params& P, float* L) {
;     ...
;     constexpr int I_F = 2816, I_LF = 3 * I_F, I_FFN = 4 * I_LF, I_IN = 32 * 101, I_OUT = 32 * 32, I_ALL = I_FFN + 2 * I_IN + 2 * I_OUT;
;     for (int it = gw; it < I_ALL; it += NGW) {
;         int r = it;
;         if (r < I_FFN) {
;             const int lf = r / I_LF, q = r % I_LF, which = q / I_F, item = q % I_F;
;             if (which == 0) transpose_item64(P.ffn_w1 + (size_t)lf * DM * FF, DM, FF, W13 + (size_t)lf * NUP * DM, 1, scr, item, lane);
;             else if (which == 1) transpose_item64(P.ffn_w3 + (size_t)lf * DM * FF, DM, FF, W13 + (size_t)lf * NUP * DM, 2, scr, item, lane);
;             else transpose_item64(P.ffn_w2 + (size_t)lf * FF * DM, FF, DM, W2 + (size_t)lf * DM * FF, 0, scr, item, lane);
;         } else {
;             r -= I_FFN;
;             if (r < 2 * I_IN) { const int l = r / I_IN, item = r % I_IN; transpose_item64(P.w_in + (size_t)l * DM * NIN, DM, NIN, WIN + (size_t)l * NINP_W * DM, 3, scr, item, lane); }
;             else { r -= 2 * I_IN; const int l = r / I_OUT, item = r % I_OUT; transpose_item64(P.w_out + (size_t)l * DM * DM, DM, DM, WOUT + (size_t)l * DM * DM, 0, scr, item, lane); }
;         }
.Lhk_n0:
	s_cmp_eq_u32 s36, 5
	s_cbranch_scc0 .Lhk_n1
	s_cmp_ge_u32 s2, 168
	s_cbranch_scc0 .Lhk_n1
	s_cmp_lt_u32 s2, 256
	s_cbranch_scc0 .Lhk_n1
	s_mov_b32 s0, 168
	s_mov_b32 s1, 88
	s_mov_b32 s99, 40256
	s_mov_b32 s98, 1024
	s_mov_b32 s100, 0x1d00
	s_mov_b32 s19, 7252
	s_branch .Lhk_go
.Lhk_n1:
	s_cmp_eq_u32 s36, 7
	s_cbranch_scc0 .Lhk_n2
	s_cmp_ge_u32 s2, 192
	s_cbranch_scc0 .Lhk_n2
	s_cmp_lt_u32 s2, 224
	s_cbranch_scc0 .Lhk_n2
	s_mov_b32 s0, 192
	s_mov_b32 s1, 32
	s_mov_b32 s99, 14676
	s_mov_b32 s98, 4800
	s_mov_b32 s100, 0xffffed40
	s_mov_b32 s19, 4800
	s_branch .Lhk_go
.Lhk_n2:
	s_cmp_eq_u32 s36, 7
	s_cbranch_scc0 .Lhk_n3
	s_cmp_ge_u32 s2, 224
	s_cbranch_scc0 .Lhk_n3
	s_cmp_lt_u32 s2, 256
	s_cbranch_scc0 .Lhk_n3
	s_mov_b32 s0, 224
	s_mov_b32 s1, 32
	s_mov_b32 s99, 19476
	s_mov_b32 s98, 5868
	s_mov_b32 s100, 0x79b4
	s_mov_b32 s19, 9100
	s_branch .Lhk_go
.Lhk_n3:
	s_cmp_eq_u32 s36, 19
	s_cbranch_scc0 .Lhk_n4
	s_cmp_ge_u32 s2, 192
	s_cbranch_scc0 .Lhk_n4
	s_cmp_lt_u32 s2, 224
	s_cbranch_scc0 .Lhk_n4
	s_mov_b32 s0, 192
	s_mov_b32 s1, 32
	s_mov_b32 s99, 25344
	s_mov_b32 s98, 3200
	s_mov_b32 s100, 0xfffff380
	s_mov_b32 s19, 3200
	s_branch .Lhk_go
.Lhk_n4:
	s_cmp_eq_u32 s36, 19
	s_cbranch_scc0 .Lhk_n5
	s_cmp_ge_u32 s2, 224
	s_cbranch_scc0 .Lhk_n5
	s_cmp_lt_u32 s2, 256
	s_cbranch_scc0 .Lhk_n5
	s_mov_b32 s0, 224
	s_mov_b32 s1, 32
	s_mov_b32 s99, 28544
	s_mov_b32 s98, 5248
	s_mov_b32 s100, 0x8cc0
	s_mov_b32 s19, 6272
	s_branch .Lhk_go
